# K-loop MFMA order: Hilbert path over (B-pair, A-pair), same-accumulator k0/k1 back to back
# speedup vs baseline: 1.0151x; 1.0034x over previous
.LBB0_411:
	s_add_u32 s16, s14, 0xfffc0080
	s_addc_u32 s17, s15, -1
	s_add_i32 s51, 0, 0x10000
	s_cmp_eq_u32 s50, 12
	s_cselect_b32 s21, s9, s17
	s_cselect_b32 s20, s46, s16
	s_cselect_b32 s17, s5, s49
	s_cselect_b32 s16, s47, s48
	s_add_i32 s54, 0, 0x14000
	v_add_u32_e32 v154, s51, v181
	v_add_u32_e32 v162, s54, v181
	ds_read_b128 v[130:133], v154
	ds_read_b128 v[134:137], v154 offset:1024
	ds_read_b128 v[150:153], v154 offset:2048
	ds_read_b128 v[154:157], v154 offset:3072
	ds_read_b128 v[158:161], v162
	ds_read_b128 v[174:177], v162 offset:1024
	ds_read_b128 v[186:189], v162 offset:2048
	ds_read_b128 v[190:193], v162 offset:3072
	s_add_i32 m0, s26, 0xc000
	ds_read_b128 v[194:197], v184
	ds_read_b128 v[198:201], v184 offset:1024
	ds_read_b128 v[202:205], v184 offset:2048
	ds_read_b128 v[206:209], v184 offset:3072
	ds_read_b128 v[224:227], v184 offset:4096
	ds_read_b128 v[228:231], v184 offset:5120
	ds_read_b128 v[232:235], v184 offset:6144
	ds_read_b128 v[236:239], v184 offset:7168
	global_load_lds_dwordx4 v146, s[14:15]
	s_add_i32 m0, s26, 0xe000
	s_nop 0
	global_load_lds_dwordx4 v148, s[14:15]
	s_waitcnt vmcnt(8)
	s_waitcnt lgkmcnt(0)
	s_barrier
	s_setprio 1
	s_waitcnt lgkmcnt(0)
	v_mfma_i32_16x16x64_i8 v[126:129], v[130:133], v[194:197], v[126:129]
	v_mfma_i32_16x16x64_i8 v[126:129], v[134:137], v[198:201], v[126:129]
	v_mfma_i32_16x16x64_i8 v[110:113], v[130:133], v[202:205], v[110:113]
	v_mfma_i32_16x16x64_i8 v[110:113], v[134:137], v[206:209], v[110:113]
	v_mfma_i32_16x16x64_i8 v[102:105], v[150:153], v[202:205], v[102:105]
	v_mfma_i32_16x16x64_i8 v[102:105], v[154:157], v[206:209], v[102:105]
	v_mfma_i32_16x16x64_i8 v[122:125], v[150:153], v[194:197], v[122:125]
	v_mfma_i32_16x16x64_i8 v[122:125], v[154:157], v[198:201], v[122:125]
	v_mfma_i32_16x16x64_i8 v[118:121], v[158:161], v[194:197], v[118:121]
	v_mfma_i32_16x16x64_i8 v[118:121], v[174:177], v[198:201], v[118:121]
	v_mfma_i32_16x16x64_i8 v[114:117], v[186:189], v[194:197], v[114:117]
	v_mfma_i32_16x16x64_i8 v[114:117], v[190:193], v[198:201], v[114:117]
	v_mfma_i32_16x16x64_i8 v[98:101], v[186:189], v[202:205], v[98:101]
	v_mfma_i32_16x16x64_i8 v[98:101], v[190:193], v[206:209], v[98:101]
	v_mfma_i32_16x16x64_i8 v[106:109], v[158:161], v[202:205], v[106:109]
	v_mfma_i32_16x16x64_i8 v[106:109], v[174:177], v[206:209], v[106:109]
	v_mfma_i32_16x16x64_i8 v[90:93], v[158:161], v[224:227], v[90:93]
	v_mfma_i32_16x16x64_i8 v[90:93], v[174:177], v[228:231], v[90:93]
	v_mfma_i32_16x16x64_i8 v[82:85], v[186:189], v[224:227], v[82:85]
	v_mfma_i32_16x16x64_i8 v[82:85], v[190:193], v[228:231], v[82:85]
	v_mfma_i32_16x16x64_i8 v[66:69], v[186:189], v[232:235], v[66:69]
	v_mfma_i32_16x16x64_i8 v[66:69], v[190:193], v[236:239], v[66:69]
	v_mfma_i32_16x16x64_i8 v[74:77], v[158:161], v[232:235], v[74:77]
	v_mfma_i32_16x16x64_i8 v[74:77], v[174:177], v[236:239], v[74:77]
	v_mfma_i32_16x16x64_i8 v[70:73], v[150:153], v[232:235], v[70:73]
	v_mfma_i32_16x16x64_i8 v[70:73], v[154:157], v[236:239], v[70:73]
	v_mfma_i32_16x16x64_i8 v[86:89], v[150:153], v[224:227], v[86:89]
	v_mfma_i32_16x16x64_i8 v[86:89], v[154:157], v[228:231], v[86:89]
	v_mfma_i32_16x16x64_i8 v[94:97], v[130:133], v[224:227], v[94:97]
	v_mfma_i32_16x16x64_i8 v[94:97], v[134:137], v[228:231], v[94:97]
	v_mfma_i32_16x16x64_i8 v[78:81], v[130:133], v[232:235], v[78:81]
	v_mfma_i32_16x16x64_i8 v[78:81], v[134:137], v[236:239], v[78:81]
	s_setprio 0
	s_barrier
	s_add_i32 s51, s51, s33
	v_lshl_add_u64 v[162:163], s[16:17], 0, v[0:1]
	s_mov_b32 m0, s51
	ds_read_b128 v[194:197], v184 offset:16384
	ds_read_b128 v[198:201], v184 offset:17408
	ds_read_b128 v[202:205], v184 offset:18432
	ds_read_b128 v[206:209], v184 offset:19456
	ds_read_b128 v[224:227], v184 offset:20480
	ds_read_b128 v[228:231], v184 offset:21504
	ds_read_b128 v[232:235], v184 offset:22528
	ds_read_b128 v[236:239], v184 offset:23552
	global_load_lds_dwordx4 v[162:163], off
	s_add_i32 m0, s51, 0x2000
	s_add_u32 s52, s16, 0x40000
	v_lshl_add_u64 v[164:165], s[16:17], 0, v[138:139]
	s_addc_u32 s53, s17, 0
	s_add_i32 s51, s54, s33
	global_load_lds_dwordx4 v[164:165], off
	s_mov_b32 m0, s51
	v_lshl_add_u64 v[168:169], s[20:21], 0, v[140:141]
	global_load_lds_dwordx4 v0, s[52:53]
	s_add_i32 m0, s51, 0x2000
	s_nop 0
	global_load_lds_dwordx4 v138, s[52:53]
	v_lshl_add_u64 v[166:167], s[20:21], 0, v[142:143]
	s_mov_b32 m0, s26
	s_nop 0
	global_load_lds_dwordx4 v[166:167], off
	s_mov_b32 m0, s27
	s_nop 0
	global_load_lds_dwordx4 v[168:169], off
	s_waitcnt vmcnt(8)
	s_waitcnt lgkmcnt(0)
	s_barrier
	s_setprio 1
	s_waitcnt lgkmcnt(0)
	v_mfma_i32_16x16x64_i8 v[62:65], v[130:133], v[194:197], v[62:65]
	v_mfma_i32_16x16x64_i8 v[62:65], v[134:137], v[198:201], v[62:65]
	v_mfma_i32_16x16x64_i8 v[46:49], v[130:133], v[202:205], v[46:49]
	v_mfma_i32_16x16x64_i8 v[46:49], v[134:137], v[206:209], v[46:49]
	v_mfma_i32_16x16x64_i8 v[38:41], v[150:153], v[202:205], v[38:41]
	v_mfma_i32_16x16x64_i8 v[38:41], v[154:157], v[206:209], v[38:41]
	v_mfma_i32_16x16x64_i8 v[54:57], v[150:153], v[194:197], v[54:57]
	v_mfma_i32_16x16x64_i8 v[54:57], v[154:157], v[198:201], v[54:57]
	v_mfma_i32_16x16x64_i8 v[58:61], v[158:161], v[194:197], v[58:61]
	v_mfma_i32_16x16x64_i8 v[58:61], v[174:177], v[198:201], v[58:61]
	v_mfma_i32_16x16x64_i8 v[50:53], v[186:189], v[194:197], v[50:53]
	v_mfma_i32_16x16x64_i8 v[50:53], v[190:193], v[198:201], v[50:53]
	v_mfma_i32_16x16x64_i8 v[34:37], v[186:189], v[202:205], v[34:37]
	v_mfma_i32_16x16x64_i8 v[34:37], v[190:193], v[206:209], v[34:37]
	v_mfma_i32_16x16x64_i8 v[42:45], v[158:161], v[202:205], v[42:45]
	v_mfma_i32_16x16x64_i8 v[42:45], v[174:177], v[206:209], v[42:45]
	v_mfma_i32_16x16x64_i8 v[26:29], v[158:161], v[224:227], v[26:29]
	v_mfma_i32_16x16x64_i8 v[26:29], v[174:177], v[228:231], v[26:29]
	v_mfma_i32_16x16x64_i8 v[18:21], v[186:189], v[224:227], v[18:21]
	v_mfma_i32_16x16x64_i8 v[18:21], v[190:193], v[228:231], v[18:21]
	v_mfma_i32_16x16x64_i8 v[2:5], v[186:189], v[232:235], v[2:5]
	v_mfma_i32_16x16x64_i8 v[2:5], v[190:193], v[236:239], v[2:5]
	v_mfma_i32_16x16x64_i8 v[10:13], v[158:161], v[232:235], v[10:13]
	v_mfma_i32_16x16x64_i8 v[10:13], v[174:177], v[236:239], v[10:13]
	v_mfma_i32_16x16x64_i8 v[6:9], v[150:153], v[232:235], v[6:9]
	v_mfma_i32_16x16x64_i8 v[6:9], v[154:157], v[236:239], v[6:9]
	v_mfma_i32_16x16x64_i8 v[22:25], v[150:153], v[224:227], v[22:25]
	v_mfma_i32_16x16x64_i8 v[22:25], v[154:157], v[228:231], v[22:25]
	v_mfma_i32_16x16x64_i8 v[30:33], v[130:133], v[224:227], v[30:33]
	v_mfma_i32_16x16x64_i8 v[30:33], v[134:137], v[228:231], v[30:33]
	v_mfma_i32_16x16x64_i8 v[14:17], v[130:133], v[232:235], v[14:17]
	v_mfma_i32_16x16x64_i8 v[14:17], v[134:137], v[236:239], v[14:17]
	s_setprio 0
	s_barrier
	s_add_i32 s51, 0, 0x18000
	s_add_i32 s52, 0, 0x1c000
	v_add_u32_e32 v154, s51, v181
	v_add_u32_e32 v170, s52, v181
	ds_read_b128 v[130:133], v154
	ds_read_b128 v[134:137], v154 offset:1024
	ds_read_b128 v[150:153], v154 offset:2048
	ds_read_b128 v[154:157], v154 offset:3072
	ds_read_b128 v[158:161], v170
	ds_read_b128 v[174:177], v170 offset:1024
	ds_read_b128 v[186:189], v170 offset:2048
	ds_read_b128 v[190:193], v170 offset:3072
	s_add_u32 s20, s20, 0x40000
	s_addc_u32 s21, s21, 0
	s_mov_b32 m0, s28
	ds_read_b128 v[194:197], v184 offset:32768
	ds_read_b128 v[198:201], v184 offset:33792
	ds_read_b128 v[202:205], v184 offset:34816
	ds_read_b128 v[206:209], v184 offset:35840
	ds_read_b128 v[224:227], v184 offset:36864
	ds_read_b128 v[228:231], v184 offset:37888
	ds_read_b128 v[232:235], v184 offset:38912
	ds_read_b128 v[236:239], v184 offset:39936
	global_load_lds_dwordx4 v142, s[20:21]
	s_mov_b32 m0, s29
	s_nop 0
	global_load_lds_dwordx4 v140, s[20:21]
	s_waitcnt vmcnt(8)
	s_waitcnt lgkmcnt(0)
	s_barrier
	s_setprio 1
	s_waitcnt lgkmcnt(0)
	v_mfma_i32_16x16x64_i8 v[126:129], v[130:133], v[194:197], v[126:129]
	v_mfma_i32_16x16x64_i8 v[126:129], v[134:137], v[198:201], v[126:129]
	v_mfma_i32_16x16x64_i8 v[110:113], v[130:133], v[202:205], v[110:113]
	v_mfma_i32_16x16x64_i8 v[110:113], v[134:137], v[206:209], v[110:113]
	v_mfma_i32_16x16x64_i8 v[102:105], v[150:153], v[202:205], v[102:105]
	v_mfma_i32_16x16x64_i8 v[102:105], v[154:157], v[206:209], v[102:105]
	v_mfma_i32_16x16x64_i8 v[122:125], v[150:153], v[194:197], v[122:125]
	v_mfma_i32_16x16x64_i8 v[122:125], v[154:157], v[198:201], v[122:125]
	v_mfma_i32_16x16x64_i8 v[118:121], v[158:161], v[194:197], v[118:121]
	v_mfma_i32_16x16x64_i8 v[118:121], v[174:177], v[198:201], v[118:121]
	v_mfma_i32_16x16x64_i8 v[114:117], v[186:189], v[194:197], v[114:117]
	v_mfma_i32_16x16x64_i8 v[114:117], v[190:193], v[198:201], v[114:117]
	v_mfma_i32_16x16x64_i8 v[98:101], v[186:189], v[202:205], v[98:101]
	v_mfma_i32_16x16x64_i8 v[98:101], v[190:193], v[206:209], v[98:101]
	v_mfma_i32_16x16x64_i8 v[106:109], v[158:161], v[202:205], v[106:109]
	v_mfma_i32_16x16x64_i8 v[106:109], v[174:177], v[206:209], v[106:109]
	v_mfma_i32_16x16x64_i8 v[90:93], v[158:161], v[224:227], v[90:93]
	v_mfma_i32_16x16x64_i8 v[90:93], v[174:177], v[228:231], v[90:93]
	v_mfma_i32_16x16x64_i8 v[82:85], v[186:189], v[224:227], v[82:85]
	v_mfma_i32_16x16x64_i8 v[82:85], v[190:193], v[228:231], v[82:85]
	v_mfma_i32_16x16x64_i8 v[66:69], v[186:189], v[232:235], v[66:69]
	v_mfma_i32_16x16x64_i8 v[66:69], v[190:193], v[236:239], v[66:69]
	v_mfma_i32_16x16x64_i8 v[74:77], v[158:161], v[232:235], v[74:77]
	v_mfma_i32_16x16x64_i8 v[74:77], v[174:177], v[236:239], v[74:77]
	v_mfma_i32_16x16x64_i8 v[70:73], v[150:153], v[232:235], v[70:73]
	v_mfma_i32_16x16x64_i8 v[70:73], v[154:157], v[236:239], v[70:73]
	v_mfma_i32_16x16x64_i8 v[86:89], v[150:153], v[224:227], v[86:89]
	v_mfma_i32_16x16x64_i8 v[86:89], v[154:157], v[228:231], v[86:89]
	v_mfma_i32_16x16x64_i8 v[94:97], v[130:133], v[224:227], v[94:97]
	v_mfma_i32_16x16x64_i8 v[94:97], v[134:137], v[228:231], v[94:97]
	v_mfma_i32_16x16x64_i8 v[78:81], v[130:133], v[232:235], v[78:81]
	v_mfma_i32_16x16x64_i8 v[78:81], v[134:137], v[236:239], v[78:81]
	s_setprio 0
	s_barrier
	s_add_i32 s20, s51, s33
	v_lshl_add_u64 v[162:163], v[162:163], 0, s[30:31]
	s_mov_b32 m0, s20
	ds_read_b128 v[194:197], v184 offset:49152
	ds_read_b128 v[198:201], v184 offset:50176
	ds_read_b128 v[202:205], v184 offset:51200
	ds_read_b128 v[206:209], v184 offset:52224
	ds_read_b128 v[224:227], v184 offset:53248
	ds_read_b128 v[228:231], v184 offset:54272
	ds_read_b128 v[232:235], v184 offset:55296
	ds_read_b128 v[236:239], v184 offset:56320
	global_load_lds_dwordx4 v[162:163], off
	s_add_i32 m0, s20, 0x2000
	s_add_u32 s16, s16, 0x40080
	v_lshl_add_u64 v[162:163], v[164:165], 0, s[30:31]
	s_addc_u32 s17, s17, 0
	s_add_i32 s20, s52, s33
	global_load_lds_dwordx4 v[162:163], off
	s_mov_b32 m0, s20
	s_nop 0
	global_load_lds_dwordx4 v0, s[16:17]
	s_add_i32 m0, s20, 0x2000
	s_nop 0
	global_load_lds_dwordx4 v138, s[16:17]
	v_lshl_add_u64 v[162:163], v[166:167], 0, s[30:31]
	s_mov_b32 m0, s34
	s_nop 0
	global_load_lds_dwordx4 v[162:163], off
	v_lshl_add_u64 v[162:163], v[168:169], 0, s[30:31]
	s_mov_b32 m0, s35
	s_nop 0
	global_load_lds_dwordx4 v[162:163], off
	s_waitcnt vmcnt(8)
	s_waitcnt lgkmcnt(0)
	s_barrier
	s_setprio 1
	s_waitcnt lgkmcnt(0)
	v_mfma_i32_16x16x64_i8 v[62:65], v[130:133], v[194:197], v[62:65]
	v_mfma_i32_16x16x64_i8 v[62:65], v[134:137], v[198:201], v[62:65]
	v_mfma_i32_16x16x64_i8 v[46:49], v[130:133], v[202:205], v[46:49]
	v_mfma_i32_16x16x64_i8 v[46:49], v[134:137], v[206:209], v[46:49]
	v_mfma_i32_16x16x64_i8 v[38:41], v[150:153], v[202:205], v[38:41]
	v_mfma_i32_16x16x64_i8 v[38:41], v[154:157], v[206:209], v[38:41]
	v_mfma_i32_16x16x64_i8 v[54:57], v[150:153], v[194:197], v[54:57]
	v_mfma_i32_16x16x64_i8 v[54:57], v[154:157], v[198:201], v[54:57]
	v_mfma_i32_16x16x64_i8 v[58:61], v[158:161], v[194:197], v[58:61]
	v_mfma_i32_16x16x64_i8 v[58:61], v[174:177], v[198:201], v[58:61]
	v_mfma_i32_16x16x64_i8 v[50:53], v[186:189], v[194:197], v[50:53]
	v_mfma_i32_16x16x64_i8 v[50:53], v[190:193], v[198:201], v[50:53]
	v_mfma_i32_16x16x64_i8 v[34:37], v[186:189], v[202:205], v[34:37]
	v_mfma_i32_16x16x64_i8 v[34:37], v[190:193], v[206:209], v[34:37]
	v_mfma_i32_16x16x64_i8 v[42:45], v[158:161], v[202:205], v[42:45]
	v_mfma_i32_16x16x64_i8 v[42:45], v[174:177], v[206:209], v[42:45]
	v_mfma_i32_16x16x64_i8 v[26:29], v[158:161], v[224:227], v[26:29]
	v_mfma_i32_16x16x64_i8 v[26:29], v[174:177], v[228:231], v[26:29]
	v_mfma_i32_16x16x64_i8 v[18:21], v[186:189], v[224:227], v[18:21]
	v_mfma_i32_16x16x64_i8 v[18:21], v[190:193], v[228:231], v[18:21]
	v_mfma_i32_16x16x64_i8 v[2:5], v[186:189], v[232:235], v[2:5]
	v_mfma_i32_16x16x64_i8 v[2:5], v[190:193], v[236:239], v[2:5]
	v_mfma_i32_16x16x64_i8 v[10:13], v[158:161], v[232:235], v[10:13]
	v_mfma_i32_16x16x64_i8 v[10:13], v[174:177], v[236:239], v[10:13]
	v_mfma_i32_16x16x64_i8 v[6:9], v[150:153], v[232:235], v[6:9]
	v_mfma_i32_16x16x64_i8 v[6:9], v[154:157], v[236:239], v[6:9]
	v_mfma_i32_16x16x64_i8 v[22:25], v[150:153], v[224:227], v[22:25]
	v_mfma_i32_16x16x64_i8 v[22:25], v[154:157], v[228:231], v[22:25]
	v_mfma_i32_16x16x64_i8 v[30:33], v[130:133], v[224:227], v[30:33]
	v_mfma_i32_16x16x64_i8 v[30:33], v[134:137], v[228:231], v[30:33]
	v_mfma_i32_16x16x64_i8 v[14:17], v[130:133], v[232:235], v[14:17]
	v_mfma_i32_16x16x64_i8 v[14:17], v[134:137], v[236:239], v[14:17]
	s_setprio 0
	s_barrier
	s_add_i32 s50, s50, 2
	s_add_u32 s14, s14, 0x100
	s_addc_u32 s15, s15, 0
	s_add_u32 s48, s48, 0x100
	s_addc_u32 s49, s49, 0
	s_cmp_gt_u32 s50, 13
	s_cbranch_scc0 .LBB0_411
	v_readlane_b32 s14, v253, 2
	v_readlane_b32 s15, v253, 3
	s_and_b64 vcc, exec, s[14:15]
	s_cbranch_vccz .LBB0_414
	s_barrier

.LBB0_493:
	s_add_u32 s16, s12, 0x100
	s_addc_u32 s17, s13, 0
	s_add_i32 s67, 0, 0x10000
	s_cmpk_eq_i32 s19, 0x54
	s_cselect_b32 s23, s7, s17
	s_cselect_b32 s22, s6, s16
	s_cselect_b32 s21, s11, s18
	s_cselect_b32 s20, s10, s15
	s_add_i32 s68, 0, 0x14000
	v_add_u32_e32 v142, s67, v205
	v_add_u32_e32 v162, s68, v205
	ds_read_b128 v[130:133], v142
	ds_read_b128 v[134:137], v142 offset:1024
	ds_read_b128 v[138:141], v142 offset:2048
	ds_read_b128 v[142:145], v142 offset:3072
	ds_read_b128 v[146:149], v162
	ds_read_b128 v[150:153], v162 offset:1024
	ds_read_b128 v[154:157], v162 offset:2048
	ds_read_b128 v[184:187], v162 offset:3072
	s_add_i32 m0, s28, 0xc000
	ds_read_b128 v[188:191], v230
	ds_read_b128 v[192:195], v230 offset:1024
	ds_read_b128 v[196:199], v230 offset:2048
	ds_read_b128 v[200:203], v230 offset:3072
	ds_read_b128 v[232:235], v230 offset:4096
	ds_read_b128 v[236:239], v230 offset:5120
	ds_read_b128 v[240:243], v230 offset:6144
	ds_read_b128 v[244:247], v230 offset:7168
	global_load_lds_dwordx4 v180, s[12:13]
	s_add_i32 m0, s28, 0xe000
	s_nop 0
	global_load_lds_dwordx4 v182, s[12:13]
	s_waitcnt vmcnt(8)
	s_waitcnt lgkmcnt(0)
	s_barrier
	s_setprio 1
	s_waitcnt lgkmcnt(0)
	v_mfma_f32_16x16x32_bf16 v[126:129], v[130:133], v[188:191], v[126:129]
	v_mfma_f32_16x16x32_bf16 v[126:129], v[134:137], v[192:195], v[126:129]
	v_mfma_f32_16x16x32_bf16 v[118:121], v[130:133], v[196:199], v[118:121]
	v_mfma_f32_16x16x32_bf16 v[118:121], v[134:137], v[200:203], v[118:121]
	v_mfma_f32_16x16x32_bf16 v[86:89], v[138:141], v[196:199], v[86:89]
	v_mfma_f32_16x16x32_bf16 v[86:89], v[142:145], v[200:203], v[86:89]
	v_mfma_f32_16x16x32_bf16 v[74:77], v[138:141], v[188:191], v[74:77]
	v_mfma_f32_16x16x32_bf16 v[74:77], v[142:145], v[192:195], v[74:77]
	v_mfma_f32_16x16x32_bf16 v[122:125], v[146:149], v[188:191], v[122:125]
	v_mfma_f32_16x16x32_bf16 v[122:125], v[150:153], v[192:195], v[122:125]
	v_mfma_f32_16x16x32_bf16 v[82:85], v[154:157], v[188:191], v[82:85]
	v_mfma_f32_16x16x32_bf16 v[82:85], v[184:187], v[192:195], v[82:85]
	v_mfma_f32_16x16x32_bf16 v[90:93], v[154:157], v[196:199], v[90:93]
	v_mfma_f32_16x16x32_bf16 v[90:93], v[184:187], v[200:203], v[90:93]
	v_mfma_f32_16x16x32_bf16 v[114:117], v[146:149], v[196:199], v[114:117]
	v_mfma_f32_16x16x32_bf16 v[114:117], v[150:153], v[200:203], v[114:117]
	v_mfma_f32_16x16x32_bf16 v[106:109], v[146:149], v[232:235], v[106:109]
	v_mfma_f32_16x16x32_bf16 v[106:109], v[150:153], v[236:239], v[106:109]
	v_mfma_f32_16x16x32_bf16 v[70:73], v[154:157], v[232:235], v[70:73]
	v_mfma_f32_16x16x32_bf16 v[70:73], v[184:187], v[236:239], v[70:73]
	v_mfma_f32_16x16x32_bf16 v[42:45], v[154:157], v[240:243], v[42:45]
	v_mfma_f32_16x16x32_bf16 v[42:45], v[184:187], v[244:247], v[42:45]
	v_mfma_f32_16x16x32_bf16 v[98:101], v[146:149], v[240:243], v[98:101]
	v_mfma_f32_16x16x32_bf16 v[98:101], v[150:153], v[244:247], v[98:101]
	v_mfma_f32_16x16x32_bf16 v[38:41], v[138:141], v[240:243], v[38:41]
	v_mfma_f32_16x16x32_bf16 v[38:41], v[142:145], v[244:247], v[38:41]
	v_mfma_f32_16x16x32_bf16 v[66:69], v[138:141], v[232:235], v[66:69]
	v_mfma_f32_16x16x32_bf16 v[66:69], v[142:145], v[236:239], v[66:69]
	v_mfma_f32_16x16x32_bf16 v[110:113], v[130:133], v[232:235], v[110:113]
	v_mfma_f32_16x16x32_bf16 v[110:113], v[134:137], v[236:239], v[110:113]
	v_mfma_f32_16x16x32_bf16 v[102:105], v[130:133], v[240:243], v[102:105]
	v_mfma_f32_16x16x32_bf16 v[102:105], v[134:137], v[244:247], v[102:105]
	s_setprio 0
	s_barrier
	s_add_i32 s12, s67, s33
	v_lshl_add_u64 v[162:163], s[20:21], 0, v[0:1]
	s_mov_b32 m0, s12
	ds_read_b128 v[188:191], v230 offset:16384
	ds_read_b128 v[192:195], v230 offset:17408
	ds_read_b128 v[196:199], v230 offset:18432
	ds_read_b128 v[200:203], v230 offset:19456
	ds_read_b128 v[232:235], v230 offset:20480
	ds_read_b128 v[236:239], v230 offset:21504
	ds_read_b128 v[240:243], v230 offset:22528
	ds_read_b128 v[244:247], v230 offset:23552
	global_load_lds_dwordx4 v[162:163], off
	s_add_i32 m0, s12, 0x2000
	s_add_u32 s12, s20, 0x160000
	v_lshl_add_u64 v[164:165], s[20:21], 0, v[158:159]
	s_addc_u32 s13, s21, 0
	s_add_i32 s67, s68, s33
	global_load_lds_dwordx4 v[164:165], off
	s_mov_b32 m0, s67
	v_lshl_add_u64 v[168:169], s[22:23], 0, v[160:161]
	global_load_lds_dwordx4 v0, s[12:13]
	s_add_i32 m0, s67, 0x2000
	s_nop 0
	global_load_lds_dwordx4 v158, s[12:13]
	v_lshl_add_u64 v[166:167], s[22:23], 0, v[174:175]
	s_mov_b32 m0, s28
	s_nop 0
	global_load_lds_dwordx4 v[166:167], off
	s_mov_b32 m0, s29
	s_nop 0
	global_load_lds_dwordx4 v[168:169], off
	s_waitcnt vmcnt(8)
	s_waitcnt lgkmcnt(0)
	s_barrier
	s_setprio 1
	s_waitcnt lgkmcnt(0)
	v_mfma_f32_16x16x32_bf16 v[94:97], v[130:133], v[188:191], v[94:97]
	v_mfma_f32_16x16x32_bf16 v[94:97], v[134:137], v[192:195], v[94:97]
	v_mfma_f32_16x16x32_bf16 v[62:65], v[130:133], v[196:199], v[62:65]
	v_mfma_f32_16x16x32_bf16 v[62:65], v[134:137], v[200:203], v[62:65]
	v_mfma_f32_16x16x32_bf16 v[30:33], v[138:141], v[196:199], v[30:33]
	v_mfma_f32_16x16x32_bf16 v[30:33], v[142:145], v[200:203], v[30:33]
	v_mfma_f32_16x16x32_bf16 v[50:53], v[138:141], v[188:191], v[50:53]
	v_mfma_f32_16x16x32_bf16 v[50:53], v[142:145], v[192:195], v[50:53]
	v_mfma_f32_16x16x32_bf16 v[78:81], v[146:149], v[188:191], v[78:81]
	v_mfma_f32_16x16x32_bf16 v[78:81], v[150:153], v[192:195], v[78:81]
	v_mfma_f32_16x16x32_bf16 v[58:61], v[154:157], v[188:191], v[58:61]
	v_mfma_f32_16x16x32_bf16 v[58:61], v[184:187], v[192:195], v[58:61]
	v_mfma_f32_16x16x32_bf16 v[34:37], v[154:157], v[196:199], v[34:37]
	v_mfma_f32_16x16x32_bf16 v[34:37], v[184:187], v[200:203], v[34:37]
	v_mfma_f32_16x16x32_bf16 v[54:57], v[146:149], v[196:199], v[54:57]
	v_mfma_f32_16x16x32_bf16 v[54:57], v[150:153], v[200:203], v[54:57]
	v_mfma_f32_16x16x32_bf16 v[26:29], v[146:149], v[232:235], v[26:29]
	v_mfma_f32_16x16x32_bf16 v[26:29], v[150:153], v[236:239], v[26:29]
	v_mfma_f32_16x16x32_bf16 v[14:17], v[154:157], v[232:235], v[14:17]
	v_mfma_f32_16x16x32_bf16 v[14:17], v[184:187], v[236:239], v[14:17]
	v_mfma_f32_16x16x32_bf16 v[6:9], v[154:157], v[240:243], v[6:9]
	v_mfma_f32_16x16x32_bf16 v[6:9], v[184:187], v[244:247], v[6:9]
	v_mfma_f32_16x16x32_bf16 v[18:21], v[146:149], v[240:243], v[18:21]
	v_mfma_f32_16x16x32_bf16 v[18:21], v[150:153], v[244:247], v[18:21]
	v_mfma_f32_16x16x32_bf16 v[2:5], v[138:141], v[240:243], v[2:5]
	v_mfma_f32_16x16x32_bf16 v[2:5], v[142:145], v[244:247], v[2:5]
	v_mfma_f32_16x16x32_bf16 v[10:13], v[138:141], v[232:235], v[10:13]
	v_mfma_f32_16x16x32_bf16 v[10:13], v[142:145], v[236:239], v[10:13]
	v_mfma_f32_16x16x32_bf16 v[46:49], v[130:133], v[232:235], v[46:49]
	v_mfma_f32_16x16x32_bf16 v[46:49], v[134:137], v[236:239], v[46:49]
	v_mfma_f32_16x16x32_bf16 v[22:25], v[130:133], v[240:243], v[22:25]
	v_mfma_f32_16x16x32_bf16 v[22:25], v[134:137], v[244:247], v[22:25]
	s_setprio 0
	s_barrier
	s_add_i32 s67, 0, 0x18000
	s_add_i32 s68, 0, 0x1c000
	v_add_u32_e32 v142, s67, v205
	v_add_u32_e32 v170, s68, v205
	ds_read_b128 v[130:133], v142
	ds_read_b128 v[134:137], v142 offset:1024
	ds_read_b128 v[138:141], v142 offset:2048
	ds_read_b128 v[142:145], v142 offset:3072
	ds_read_b128 v[146:149], v170
	ds_read_b128 v[150:153], v170 offset:1024
	ds_read_b128 v[154:157], v170 offset:2048
	ds_read_b128 v[184:187], v170 offset:3072
	s_add_u32 s12, s22, 0x160000
	s_addc_u32 s13, s23, 0
	s_mov_b32 m0, s34
	ds_read_b128 v[188:191], v230 offset:32768
	ds_read_b128 v[192:195], v230 offset:33792
	ds_read_b128 v[196:199], v230 offset:34816
	ds_read_b128 v[200:203], v230 offset:35840
	ds_read_b128 v[232:235], v230 offset:36864
	ds_read_b128 v[236:239], v230 offset:37888
	ds_read_b128 v[240:243], v230 offset:38912
	ds_read_b128 v[244:247], v230 offset:39936
	global_load_lds_dwordx4 v174, s[12:13]
	s_mov_b32 m0, s35
	s_nop 0
	global_load_lds_dwordx4 v160, s[12:13]
	s_waitcnt vmcnt(8)
	s_waitcnt lgkmcnt(0)
	s_barrier
	s_setprio 1
	s_waitcnt lgkmcnt(0)
	v_mfma_f32_16x16x32_bf16 v[126:129], v[130:133], v[188:191], v[126:129]
	v_mfma_f32_16x16x32_bf16 v[126:129], v[134:137], v[192:195], v[126:129]
	v_mfma_f32_16x16x32_bf16 v[118:121], v[130:133], v[196:199], v[118:121]
	v_mfma_f32_16x16x32_bf16 v[118:121], v[134:137], v[200:203], v[118:121]
	v_mfma_f32_16x16x32_bf16 v[86:89], v[138:141], v[196:199], v[86:89]
	v_mfma_f32_16x16x32_bf16 v[86:89], v[142:145], v[200:203], v[86:89]
	v_mfma_f32_16x16x32_bf16 v[74:77], v[138:141], v[188:191], v[74:77]
	v_mfma_f32_16x16x32_bf16 v[74:77], v[142:145], v[192:195], v[74:77]
	v_mfma_f32_16x16x32_bf16 v[122:125], v[146:149], v[188:191], v[122:125]
	v_mfma_f32_16x16x32_bf16 v[122:125], v[150:153], v[192:195], v[122:125]
	v_mfma_f32_16x16x32_bf16 v[82:85], v[154:157], v[188:191], v[82:85]
	v_mfma_f32_16x16x32_bf16 v[82:85], v[184:187], v[192:195], v[82:85]
	v_mfma_f32_16x16x32_bf16 v[90:93], v[154:157], v[196:199], v[90:93]
	v_mfma_f32_16x16x32_bf16 v[90:93], v[184:187], v[200:203], v[90:93]
	v_mfma_f32_16x16x32_bf16 v[114:117], v[146:149], v[196:199], v[114:117]
	v_mfma_f32_16x16x32_bf16 v[114:117], v[150:153], v[200:203], v[114:117]
	v_mfma_f32_16x16x32_bf16 v[106:109], v[146:149], v[232:235], v[106:109]
	v_mfma_f32_16x16x32_bf16 v[106:109], v[150:153], v[236:239], v[106:109]
	v_mfma_f32_16x16x32_bf16 v[70:73], v[154:157], v[232:235], v[70:73]
	v_mfma_f32_16x16x32_bf16 v[70:73], v[184:187], v[236:239], v[70:73]
	v_mfma_f32_16x16x32_bf16 v[42:45], v[154:157], v[240:243], v[42:45]
	v_mfma_f32_16x16x32_bf16 v[42:45], v[184:187], v[244:247], v[42:45]
	v_mfma_f32_16x16x32_bf16 v[98:101], v[146:149], v[240:243], v[98:101]
	v_mfma_f32_16x16x32_bf16 v[98:101], v[150:153], v[244:247], v[98:101]
	v_mfma_f32_16x16x32_bf16 v[38:41], v[138:141], v[240:243], v[38:41]
	v_mfma_f32_16x16x32_bf16 v[38:41], v[142:145], v[244:247], v[38:41]
	v_mfma_f32_16x16x32_bf16 v[66:69], v[138:141], v[232:235], v[66:69]
	v_mfma_f32_16x16x32_bf16 v[66:69], v[142:145], v[236:239], v[66:69]
	v_mfma_f32_16x16x32_bf16 v[110:113], v[130:133], v[232:235], v[110:113]
	v_mfma_f32_16x16x32_bf16 v[110:113], v[134:137], v[236:239], v[110:113]
	v_mfma_f32_16x16x32_bf16 v[102:105], v[130:133], v[240:243], v[102:105]
	v_mfma_f32_16x16x32_bf16 v[102:105], v[134:137], v[244:247], v[102:105]
	s_setprio 0
	s_barrier
	s_add_i32 s12, s67, s33
	v_lshl_add_u64 v[162:163], v[162:163], 0, s[30:31]
	s_mov_b32 m0, s12
	ds_read_b128 v[188:191], v230 offset:49152
	ds_read_b128 v[192:195], v230 offset:50176
	ds_read_b128 v[196:199], v230 offset:51200
	ds_read_b128 v[200:203], v230 offset:52224
	ds_read_b128 v[232:235], v230 offset:53248
	ds_read_b128 v[236:239], v230 offset:54272
	ds_read_b128 v[240:243], v230 offset:55296
	ds_read_b128 v[244:247], v230 offset:56320
	global_load_lds_dwordx4 v[162:163], off
	s_add_i32 m0, s12, 0x2000
	s_add_u32 s12, s20, 0x160080
	v_lshl_add_u64 v[162:163], v[164:165], 0, s[30:31]
	s_addc_u32 s13, s21, 0
	s_add_i32 s20, s68, s33
	global_load_lds_dwordx4 v[162:163], off
	s_mov_b32 m0, s20
	s_nop 0
	global_load_lds_dwordx4 v0, s[12:13]
	s_add_i32 m0, s20, 0x2000
	s_nop 0
	global_load_lds_dwordx4 v158, s[12:13]
	v_lshl_add_u64 v[162:163], v[166:167], 0, s[30:31]
	s_mov_b32 m0, s55
	s_nop 0
	global_load_lds_dwordx4 v[162:163], off
	v_lshl_add_u64 v[162:163], v[168:169], 0, s[30:31]
	s_mov_b32 m0, s56
	s_nop 0
	global_load_lds_dwordx4 v[162:163], off
	s_waitcnt vmcnt(8)
	s_waitcnt lgkmcnt(0)
	s_barrier
	s_setprio 1
	s_waitcnt lgkmcnt(0)
	v_mfma_f32_16x16x32_bf16 v[94:97], v[130:133], v[188:191], v[94:97]
	v_mfma_f32_16x16x32_bf16 v[94:97], v[134:137], v[192:195], v[94:97]
	v_mfma_f32_16x16x32_bf16 v[62:65], v[130:133], v[196:199], v[62:65]
	v_mfma_f32_16x16x32_bf16 v[62:65], v[134:137], v[200:203], v[62:65]
	v_mfma_f32_16x16x32_bf16 v[30:33], v[138:141], v[196:199], v[30:33]
	v_mfma_f32_16x16x32_bf16 v[30:33], v[142:145], v[200:203], v[30:33]
	v_mfma_f32_16x16x32_bf16 v[50:53], v[138:141], v[188:191], v[50:53]
	v_mfma_f32_16x16x32_bf16 v[50:53], v[142:145], v[192:195], v[50:53]
	v_mfma_f32_16x16x32_bf16 v[78:81], v[146:149], v[188:191], v[78:81]
	v_mfma_f32_16x16x32_bf16 v[78:81], v[150:153], v[192:195], v[78:81]
	v_mfma_f32_16x16x32_bf16 v[58:61], v[154:157], v[188:191], v[58:61]
	v_mfma_f32_16x16x32_bf16 v[58:61], v[184:187], v[192:195], v[58:61]
	v_mfma_f32_16x16x32_bf16 v[34:37], v[154:157], v[196:199], v[34:37]
	v_mfma_f32_16x16x32_bf16 v[34:37], v[184:187], v[200:203], v[34:37]
	v_mfma_f32_16x16x32_bf16 v[54:57], v[146:149], v[196:199], v[54:57]
	v_mfma_f32_16x16x32_bf16 v[54:57], v[150:153], v[200:203], v[54:57]
	v_mfma_f32_16x16x32_bf16 v[26:29], v[146:149], v[232:235], v[26:29]
	v_mfma_f32_16x16x32_bf16 v[26:29], v[150:153], v[236:239], v[26:29]
	v_mfma_f32_16x16x32_bf16 v[14:17], v[154:157], v[232:235], v[14:17]
	v_mfma_f32_16x16x32_bf16 v[14:17], v[184:187], v[236:239], v[14:17]
	v_mfma_f32_16x16x32_bf16 v[6:9], v[154:157], v[240:243], v[6:9]
	v_mfma_f32_16x16x32_bf16 v[6:9], v[184:187], v[244:247], v[6:9]
	v_mfma_f32_16x16x32_bf16 v[18:21], v[146:149], v[240:243], v[18:21]
	v_mfma_f32_16x16x32_bf16 v[18:21], v[150:153], v[244:247], v[18:21]
	v_mfma_f32_16x16x32_bf16 v[2:5], v[138:141], v[240:243], v[2:5]
	v_mfma_f32_16x16x32_bf16 v[2:5], v[142:145], v[244:247], v[2:5]
	v_mfma_f32_16x16x32_bf16 v[10:13], v[138:141], v[232:235], v[10:13]
	v_mfma_f32_16x16x32_bf16 v[10:13], v[142:145], v[236:239], v[10:13]
	v_mfma_f32_16x16x32_bf16 v[46:49], v[130:133], v[232:235], v[46:49]
	v_mfma_f32_16x16x32_bf16 v[46:49], v[134:137], v[236:239], v[46:49]
	v_mfma_f32_16x16x32_bf16 v[22:25], v[130:133], v[240:243], v[22:25]
	v_mfma_f32_16x16x32_bf16 v[22:25], v[134:137], v[244:247], v[22:25]
	s_setprio 0
	s_barrier
	s_add_i32 s19, s19, 2
	s_add_u32 s15, s15, 0x100
	s_addc_u32 s18, s18, 0
	s_cmpk_gt_u32 s19, 0x55
	s_mov_b64 s[12:13], s[16:17]
	s_cbranch_scc0 .LBB0_493
	v_readlane_b32 s12, v253, 2
	v_readlane_b32 s13, v253, 3
	s_and_b64 vcc, exec, s[12:13]
	s_cbranch_vccz .LBB0_496
	s_barrier

.LBB0_641:
	s_add_u32 s28, s26, 0xfffc0080
	s_addc_u32 s29, s27, -1
	s_add_i32 s57, 0, 0x10000
	s_cmp_eq_u32 s56, 12
	s_cselect_b32 s43, s15, s29
	s_cselect_b32 s42, s19, s28
	s_cselect_b32 s29, s11, s55
	s_cselect_b32 s28, s53, s54
	s_add_i32 s60, 0, 0x14000
	v_add_u32_e32 v152, s57, v159
	v_add_u32_e32 v156, s60, v159
	ds_read_b128 v[140:143], v152
	ds_read_b128 v[144:147], v152 offset:1024
	ds_read_b128 v[148:151], v152 offset:2048
	ds_read_b128 v[152:155], v152 offset:3072
	ds_read_b128 v[176:179], v156
	ds_read_b128 v[180:183], v156 offset:1024
	ds_read_b128 v[184:187], v156 offset:2048
	ds_read_b128 v[188:191], v156 offset:3072
	s_add_i32 m0, s44, 0xc000
	ds_read_b128 v[192:195], v174
	ds_read_b128 v[196:199], v174 offset:1024
	ds_read_b128 v[200:203], v174 offset:2048
	ds_read_b128 v[204:207], v174 offset:3072
	ds_read_b128 v[208:211], v174 offset:4096
	ds_read_b128 v[224:227], v174 offset:5120
	ds_read_b128 v[228:231], v174 offset:6144
	ds_read_b128 v[232:235], v174 offset:7168
	global_load_lds_dwordx4 v136, s[26:27]
	s_add_i32 m0, s44, 0xe000
	s_nop 0
	global_load_lds_dwordx4 v138, s[26:27]
	s_waitcnt vmcnt(8)
	s_waitcnt lgkmcnt(0)
	s_barrier
	s_setprio 1
	s_waitcnt lgkmcnt(0)
	v_mfma_i32_16x16x64_i8 v[126:129], v[140:143], v[192:195], v[126:129]
	v_mfma_i32_16x16x64_i8 v[126:129], v[144:147], v[196:199], v[126:129]
	v_mfma_i32_16x16x64_i8 v[110:113], v[140:143], v[200:203], v[110:113]
	v_mfma_i32_16x16x64_i8 v[110:113], v[144:147], v[204:207], v[110:113]
	v_mfma_i32_16x16x64_i8 v[106:109], v[148:151], v[200:203], v[106:109]
	v_mfma_i32_16x16x64_i8 v[106:109], v[152:155], v[204:207], v[106:109]
	v_mfma_i32_16x16x64_i8 v[122:125], v[148:151], v[192:195], v[122:125]
	v_mfma_i32_16x16x64_i8 v[122:125], v[152:155], v[196:199], v[122:125]
	v_mfma_i32_16x16x64_i8 v[118:121], v[176:179], v[192:195], v[118:121]
	v_mfma_i32_16x16x64_i8 v[118:121], v[180:183], v[196:199], v[118:121]
	v_mfma_i32_16x16x64_i8 v[114:117], v[184:187], v[192:195], v[114:117]
	v_mfma_i32_16x16x64_i8 v[114:117], v[188:191], v[196:199], v[114:117]
	v_mfma_i32_16x16x64_i8 v[98:101], v[184:187], v[200:203], v[98:101]
	v_mfma_i32_16x16x64_i8 v[98:101], v[188:191], v[204:207], v[98:101]
	v_mfma_i32_16x16x64_i8 v[102:105], v[176:179], v[200:203], v[102:105]
	v_mfma_i32_16x16x64_i8 v[102:105], v[180:183], v[204:207], v[102:105]
	v_mfma_i32_16x16x64_i8 v[86:89], v[176:179], v[208:211], v[86:89]
	v_mfma_i32_16x16x64_i8 v[86:89], v[180:183], v[224:227], v[86:89]
	v_mfma_i32_16x16x64_i8 v[82:85], v[184:187], v[208:211], v[82:85]
	v_mfma_i32_16x16x64_i8 v[82:85], v[188:191], v[224:227], v[82:85]
	v_mfma_i32_16x16x64_i8 v[66:69], v[184:187], v[228:231], v[66:69]
	v_mfma_i32_16x16x64_i8 v[66:69], v[188:191], v[232:235], v[66:69]
	v_mfma_i32_16x16x64_i8 v[70:73], v[176:179], v[228:231], v[70:73]
	v_mfma_i32_16x16x64_i8 v[70:73], v[180:183], v[232:235], v[70:73]
	v_mfma_i32_16x16x64_i8 v[74:77], v[148:151], v[228:231], v[74:77]
	v_mfma_i32_16x16x64_i8 v[74:77], v[152:155], v[232:235], v[74:77]
	v_mfma_i32_16x16x64_i8 v[90:93], v[148:151], v[208:211], v[90:93]
	v_mfma_i32_16x16x64_i8 v[90:93], v[152:155], v[224:227], v[90:93]
	v_mfma_i32_16x16x64_i8 v[94:97], v[140:143], v[208:211], v[94:97]
	v_mfma_i32_16x16x64_i8 v[94:97], v[144:147], v[224:227], v[94:97]
	v_mfma_i32_16x16x64_i8 v[78:81], v[140:143], v[228:231], v[78:81]
	v_mfma_i32_16x16x64_i8 v[78:81], v[144:147], v[232:235], v[78:81]
	s_setprio 0
	s_barrier
	s_add_i32 s57, s57, s33
	v_lshl_add_u64 v[156:157], s[28:29], 0, v[0:1]
	s_mov_b32 m0, s57
	ds_read_b128 v[192:195], v174 offset:16384
	ds_read_b128 v[196:199], v174 offset:17408
	ds_read_b128 v[200:203], v174 offset:18432
	ds_read_b128 v[204:207], v174 offset:19456
	ds_read_b128 v[208:211], v174 offset:20480
	ds_read_b128 v[224:227], v174 offset:21504
	ds_read_b128 v[228:231], v174 offset:22528
	ds_read_b128 v[232:235], v174 offset:23552
	global_load_lds_dwordx4 v[156:157], off
	s_add_i32 m0, s57, 0x2000
	s_add_u32 s58, s28, 0x40000
	v_lshl_add_u64 v[162:163], s[28:29], 0, v[130:131]
	s_addc_u32 s59, s29, 0
	s_add_i32 s57, s60, s33
	global_load_lds_dwordx4 v[162:163], off
	s_mov_b32 m0, s57
	v_lshl_add_u64 v[166:167], s[42:43], 0, v[132:133]
	global_load_lds_dwordx4 v0, s[58:59]
	s_add_i32 m0, s57, 0x2000
	s_nop 0
	global_load_lds_dwordx4 v130, s[58:59]
	v_lshl_add_u64 v[164:165], s[42:43], 0, v[134:135]
	s_mov_b32 m0, s44
	s_nop 0
	global_load_lds_dwordx4 v[164:165], off
	s_mov_b32 m0, s45
	s_nop 0
	global_load_lds_dwordx4 v[166:167], off
	s_waitcnt vmcnt(8)
	s_waitcnt lgkmcnt(0)
	s_barrier
	s_setprio 1
	s_waitcnt lgkmcnt(0)
	v_mfma_i32_16x16x64_i8 v[62:65], v[140:143], v[192:195], v[62:65]
	v_mfma_i32_16x16x64_i8 v[62:65], v[144:147], v[196:199], v[62:65]
	v_mfma_i32_16x16x64_i8 v[46:49], v[140:143], v[200:203], v[46:49]
	v_mfma_i32_16x16x64_i8 v[46:49], v[144:147], v[204:207], v[46:49]
	v_mfma_i32_16x16x64_i8 v[42:45], v[148:151], v[200:203], v[42:45]
	v_mfma_i32_16x16x64_i8 v[42:45], v[152:155], v[204:207], v[42:45]
	v_mfma_i32_16x16x64_i8 v[58:61], v[148:151], v[192:195], v[58:61]
	v_mfma_i32_16x16x64_i8 v[58:61], v[152:155], v[196:199], v[58:61]
	v_mfma_i32_16x16x64_i8 v[54:57], v[176:179], v[192:195], v[54:57]
	v_mfma_i32_16x16x64_i8 v[54:57], v[180:183], v[196:199], v[54:57]
	v_mfma_i32_16x16x64_i8 v[50:53], v[184:187], v[192:195], v[50:53]
	v_mfma_i32_16x16x64_i8 v[50:53], v[188:191], v[196:199], v[50:53]
	v_mfma_i32_16x16x64_i8 v[34:37], v[184:187], v[200:203], v[34:37]
	v_mfma_i32_16x16x64_i8 v[34:37], v[188:191], v[204:207], v[34:37]
	v_mfma_i32_16x16x64_i8 v[38:41], v[176:179], v[200:203], v[38:41]
	v_mfma_i32_16x16x64_i8 v[38:41], v[180:183], v[204:207], v[38:41]
	v_mfma_i32_16x16x64_i8 v[22:25], v[176:179], v[208:211], v[22:25]
	v_mfma_i32_16x16x64_i8 v[22:25], v[180:183], v[224:227], v[22:25]
	v_mfma_i32_16x16x64_i8 v[18:21], v[184:187], v[208:211], v[18:21]
	v_mfma_i32_16x16x64_i8 v[18:21], v[188:191], v[224:227], v[18:21]
	v_mfma_i32_16x16x64_i8 v[2:5], v[184:187], v[228:231], v[2:5]
	v_mfma_i32_16x16x64_i8 v[2:5], v[188:191], v[232:235], v[2:5]
	v_mfma_i32_16x16x64_i8 v[6:9], v[176:179], v[228:231], v[6:9]
	v_mfma_i32_16x16x64_i8 v[6:9], v[180:183], v[232:235], v[6:9]
	v_mfma_i32_16x16x64_i8 v[10:13], v[148:151], v[228:231], v[10:13]
	v_mfma_i32_16x16x64_i8 v[10:13], v[152:155], v[232:235], v[10:13]
	v_mfma_i32_16x16x64_i8 v[26:29], v[148:151], v[208:211], v[26:29]
	v_mfma_i32_16x16x64_i8 v[26:29], v[152:155], v[224:227], v[26:29]
	v_mfma_i32_16x16x64_i8 v[30:33], v[140:143], v[208:211], v[30:33]
	v_mfma_i32_16x16x64_i8 v[30:33], v[144:147], v[224:227], v[30:33]
	v_mfma_i32_16x16x64_i8 v[14:17], v[140:143], v[228:231], v[14:17]
	v_mfma_i32_16x16x64_i8 v[14:17], v[144:147], v[232:235], v[14:17]
	s_setprio 0
	s_barrier
	s_add_i32 s57, 0, 0x18000
	s_add_i32 s58, 0, 0x1c000
	v_add_u32_e32 v152, s57, v159
	v_add_u32_e32 v168, s58, v159
	ds_read_b128 v[140:143], v152
	ds_read_b128 v[144:147], v152 offset:1024
	ds_read_b128 v[148:151], v152 offset:2048
	ds_read_b128 v[152:155], v152 offset:3072
	ds_read_b128 v[176:179], v168
	ds_read_b128 v[180:183], v168 offset:1024
	ds_read_b128 v[184:187], v168 offset:2048
	ds_read_b128 v[188:191], v168 offset:3072
	s_add_u32 s42, s42, 0x40000
	s_addc_u32 s43, s43, 0
	s_mov_b32 m0, s46
	ds_read_b128 v[192:195], v174 offset:32768
	ds_read_b128 v[196:199], v174 offset:33792
	ds_read_b128 v[200:203], v174 offset:34816
	ds_read_b128 v[204:207], v174 offset:35840
	ds_read_b128 v[208:211], v174 offset:36864
	ds_read_b128 v[224:227], v174 offset:37888
	ds_read_b128 v[228:231], v174 offset:38912
	ds_read_b128 v[232:235], v174 offset:39936
	global_load_lds_dwordx4 v134, s[42:43]
	s_mov_b32 m0, s47
	s_nop 0
	global_load_lds_dwordx4 v132, s[42:43]
	s_waitcnt vmcnt(8)
	s_waitcnt lgkmcnt(0)
	s_barrier
	s_setprio 1
	s_waitcnt lgkmcnt(0)
	v_mfma_i32_16x16x64_i8 v[126:129], v[140:143], v[192:195], v[126:129]
	v_mfma_i32_16x16x64_i8 v[126:129], v[144:147], v[196:199], v[126:129]
	v_mfma_i32_16x16x64_i8 v[110:113], v[140:143], v[200:203], v[110:113]
	v_mfma_i32_16x16x64_i8 v[110:113], v[144:147], v[204:207], v[110:113]
	v_mfma_i32_16x16x64_i8 v[106:109], v[148:151], v[200:203], v[106:109]
	v_mfma_i32_16x16x64_i8 v[106:109], v[152:155], v[204:207], v[106:109]
	v_mfma_i32_16x16x64_i8 v[122:125], v[148:151], v[192:195], v[122:125]
	v_mfma_i32_16x16x64_i8 v[122:125], v[152:155], v[196:199], v[122:125]
	v_mfma_i32_16x16x64_i8 v[118:121], v[176:179], v[192:195], v[118:121]
	v_mfma_i32_16x16x64_i8 v[118:121], v[180:183], v[196:199], v[118:121]
	v_mfma_i32_16x16x64_i8 v[114:117], v[184:187], v[192:195], v[114:117]
	v_mfma_i32_16x16x64_i8 v[114:117], v[188:191], v[196:199], v[114:117]
	v_mfma_i32_16x16x64_i8 v[98:101], v[184:187], v[200:203], v[98:101]
	v_mfma_i32_16x16x64_i8 v[98:101], v[188:191], v[204:207], v[98:101]
	v_mfma_i32_16x16x64_i8 v[102:105], v[176:179], v[200:203], v[102:105]
	v_mfma_i32_16x16x64_i8 v[102:105], v[180:183], v[204:207], v[102:105]
	v_mfma_i32_16x16x64_i8 v[86:89], v[176:179], v[208:211], v[86:89]
	v_mfma_i32_16x16x64_i8 v[86:89], v[180:183], v[224:227], v[86:89]
	v_mfma_i32_16x16x64_i8 v[82:85], v[184:187], v[208:211], v[82:85]
	v_mfma_i32_16x16x64_i8 v[82:85], v[188:191], v[224:227], v[82:85]
	v_mfma_i32_16x16x64_i8 v[66:69], v[184:187], v[228:231], v[66:69]
	v_mfma_i32_16x16x64_i8 v[66:69], v[188:191], v[232:235], v[66:69]
	v_mfma_i32_16x16x64_i8 v[70:73], v[176:179], v[228:231], v[70:73]
	v_mfma_i32_16x16x64_i8 v[70:73], v[180:183], v[232:235], v[70:73]
	v_mfma_i32_16x16x64_i8 v[74:77], v[148:151], v[228:231], v[74:77]
	v_mfma_i32_16x16x64_i8 v[74:77], v[152:155], v[232:235], v[74:77]
	v_mfma_i32_16x16x64_i8 v[90:93], v[148:151], v[208:211], v[90:93]
	v_mfma_i32_16x16x64_i8 v[90:93], v[152:155], v[224:227], v[90:93]
	v_mfma_i32_16x16x64_i8 v[94:97], v[140:143], v[208:211], v[94:97]
	v_mfma_i32_16x16x64_i8 v[94:97], v[144:147], v[224:227], v[94:97]
	v_mfma_i32_16x16x64_i8 v[78:81], v[140:143], v[228:231], v[78:81]
	v_mfma_i32_16x16x64_i8 v[78:81], v[144:147], v[232:235], v[78:81]
	s_setprio 0
	s_barrier
	s_add_i32 s42, s57, s33
	v_lshl_add_u64 v[156:157], v[156:157], 0, s[30:31]
	s_mov_b32 m0, s42
	ds_read_b128 v[192:195], v174 offset:49152
	ds_read_b128 v[196:199], v174 offset:50176
	ds_read_b128 v[200:203], v174 offset:51200
	ds_read_b128 v[204:207], v174 offset:52224
	ds_read_b128 v[208:211], v174 offset:53248
	ds_read_b128 v[224:227], v174 offset:54272
	ds_read_b128 v[228:231], v174 offset:55296
	ds_read_b128 v[232:235], v174 offset:56320
	global_load_lds_dwordx4 v[156:157], off
	s_add_i32 m0, s42, 0x2000
	s_add_u32 s28, s28, 0x40080
	v_lshl_add_u64 v[156:157], v[162:163], 0, s[30:31]
	s_addc_u32 s29, s29, 0
	s_add_i32 s42, s58, s33
	global_load_lds_dwordx4 v[156:157], off
	s_mov_b32 m0, s42
	s_nop 0
	global_load_lds_dwordx4 v0, s[28:29]
	s_add_i32 m0, s42, 0x2000
	s_nop 0
	global_load_lds_dwordx4 v130, s[28:29]
	v_lshl_add_u64 v[156:157], v[164:165], 0, s[30:31]
	s_mov_b32 m0, s48
	s_nop 0
	global_load_lds_dwordx4 v[156:157], off
	v_lshl_add_u64 v[156:157], v[166:167], 0, s[30:31]
	s_mov_b32 m0, s49
	s_nop 0
	global_load_lds_dwordx4 v[156:157], off
	s_waitcnt vmcnt(8)
	s_waitcnt lgkmcnt(0)
	s_barrier
	s_setprio 1
	s_waitcnt lgkmcnt(0)
	v_mfma_i32_16x16x64_i8 v[62:65], v[140:143], v[192:195], v[62:65]
	v_mfma_i32_16x16x64_i8 v[62:65], v[144:147], v[196:199], v[62:65]
	v_mfma_i32_16x16x64_i8 v[46:49], v[140:143], v[200:203], v[46:49]
	v_mfma_i32_16x16x64_i8 v[46:49], v[144:147], v[204:207], v[46:49]
	v_mfma_i32_16x16x64_i8 v[42:45], v[148:151], v[200:203], v[42:45]
	v_mfma_i32_16x16x64_i8 v[42:45], v[152:155], v[204:207], v[42:45]
	v_mfma_i32_16x16x64_i8 v[58:61], v[148:151], v[192:195], v[58:61]
	v_mfma_i32_16x16x64_i8 v[58:61], v[152:155], v[196:199], v[58:61]
	v_mfma_i32_16x16x64_i8 v[54:57], v[176:179], v[192:195], v[54:57]
	v_mfma_i32_16x16x64_i8 v[54:57], v[180:183], v[196:199], v[54:57]
	v_mfma_i32_16x16x64_i8 v[50:53], v[184:187], v[192:195], v[50:53]
	v_mfma_i32_16x16x64_i8 v[50:53], v[188:191], v[196:199], v[50:53]
	v_mfma_i32_16x16x64_i8 v[34:37], v[184:187], v[200:203], v[34:37]
	v_mfma_i32_16x16x64_i8 v[34:37], v[188:191], v[204:207], v[34:37]
	v_mfma_i32_16x16x64_i8 v[38:41], v[176:179], v[200:203], v[38:41]
	v_mfma_i32_16x16x64_i8 v[38:41], v[180:183], v[204:207], v[38:41]
	v_mfma_i32_16x16x64_i8 v[22:25], v[176:179], v[208:211], v[22:25]
	v_mfma_i32_16x16x64_i8 v[22:25], v[180:183], v[224:227], v[22:25]
	v_mfma_i32_16x16x64_i8 v[18:21], v[184:187], v[208:211], v[18:21]
	v_mfma_i32_16x16x64_i8 v[18:21], v[188:191], v[224:227], v[18:21]
	v_mfma_i32_16x16x64_i8 v[2:5], v[184:187], v[228:231], v[2:5]
	v_mfma_i32_16x16x64_i8 v[2:5], v[188:191], v[232:235], v[2:5]
	v_mfma_i32_16x16x64_i8 v[6:9], v[176:179], v[228:231], v[6:9]
	v_mfma_i32_16x16x64_i8 v[6:9], v[180:183], v[232:235], v[6:9]
	v_mfma_i32_16x16x64_i8 v[10:13], v[148:151], v[228:231], v[10:13]
	v_mfma_i32_16x16x64_i8 v[10:13], v[152:155], v[232:235], v[10:13]
	v_mfma_i32_16x16x64_i8 v[26:29], v[148:151], v[208:211], v[26:29]
	v_mfma_i32_16x16x64_i8 v[26:29], v[152:155], v[224:227], v[26:29]
	v_mfma_i32_16x16x64_i8 v[30:33], v[140:143], v[208:211], v[30:33]
	v_mfma_i32_16x16x64_i8 v[30:33], v[144:147], v[224:227], v[30:33]
	v_mfma_i32_16x16x64_i8 v[14:17], v[140:143], v[228:231], v[14:17]
	v_mfma_i32_16x16x64_i8 v[14:17], v[144:147], v[232:235], v[14:17]
	s_setprio 0
	s_barrier
	s_add_i32 s56, s56, 2
	s_add_u32 s26, s26, 0x100
	s_addc_u32 s27, s27, 0
	s_add_u32 s54, s54, 0x100
	s_addc_u32 s55, s55, 0
	s_cmp_gt_u32 s56, 13
	s_cbranch_scc0 .LBB0_641
	v_readlane_b32 s26, v253, 2
	v_readlane_b32 s27, v253, 3
	s_and_b64 vcc, exec, s[26:27]
	s_cbranch_vccz .LBB0_644
	s_barrier

.LBB0_665:
	s_add_u32 s16, s6, 0xfff80080
	s_addc_u32 s17, s7, -1
	s_add_i32 s57, 0, 0x10000
	s_cmp_eq_u32 s56, 28
	s_cselect_b32 s21, s9, s17
	s_cselect_b32 s20, s18, s16
	s_cselect_b32 s17, s5, s55
	s_cselect_b32 s16, s19, s54
	s_add_i32 s60, 0, 0x14000
	v_add_u32_e32 v142, s57, v193
	v_add_u32_e32 v162, s60, v193
	ds_read_b128 v[130:133], v142
	ds_read_b128 v[134:137], v142 offset:1024
	ds_read_b128 v[138:141], v142 offset:2048
	ds_read_b128 v[142:145], v142 offset:3072
	ds_read_b128 v[158:161], v162
	ds_read_b128 v[174:177], v162 offset:1024
	ds_read_b128 v[178:181], v162 offset:2048
	ds_read_b128 v[182:185], v162 offset:3072
	s_add_i32 m0, s26, 0xc000
	ds_read_b128 v[186:189], v196
	ds_read_b128 v[198:201], v196 offset:1024
	ds_read_b128 v[202:205], v196 offset:2048
	ds_read_b128 v[206:209], v196 offset:3072
	ds_read_b128 v[224:227], v196 offset:4096
	ds_read_b128 v[228:231], v196 offset:5120
	ds_read_b128 v[232:235], v196 offset:6144
	ds_read_b128 v[236:239], v196 offset:7168
	global_load_lds_dwordx4 v154, s[6:7]
	s_add_i32 m0, s26, 0xe000
	s_nop 0
	global_load_lds_dwordx4 v156, s[6:7]
	s_waitcnt vmcnt(8)
	s_waitcnt lgkmcnt(0)
	s_barrier
	s_setprio 1
	s_waitcnt lgkmcnt(0)
	v_mfma_f32_16x16x32_bf16 v[126:129], v[130:133], v[186:189], v[126:129]
	v_mfma_f32_16x16x32_bf16 v[126:129], v[134:137], v[198:201], v[126:129]
	v_mfma_f32_16x16x32_bf16 v[110:113], v[130:133], v[202:205], v[110:113]
	v_mfma_f32_16x16x32_bf16 v[110:113], v[134:137], v[206:209], v[110:113]
	v_mfma_f32_16x16x32_bf16 v[106:109], v[138:141], v[202:205], v[106:109]
	v_mfma_f32_16x16x32_bf16 v[106:109], v[142:145], v[206:209], v[106:109]
	v_mfma_f32_16x16x32_bf16 v[122:125], v[138:141], v[186:189], v[122:125]
	v_mfma_f32_16x16x32_bf16 v[122:125], v[142:145], v[198:201], v[122:125]
	v_mfma_f32_16x16x32_bf16 v[118:121], v[158:161], v[186:189], v[118:121]
	v_mfma_f32_16x16x32_bf16 v[118:121], v[174:177], v[198:201], v[118:121]
	v_mfma_f32_16x16x32_bf16 v[114:117], v[178:181], v[186:189], v[114:117]
	v_mfma_f32_16x16x32_bf16 v[114:117], v[182:185], v[198:201], v[114:117]
	v_mfma_f32_16x16x32_bf16 v[98:101], v[178:181], v[202:205], v[98:101]
	v_mfma_f32_16x16x32_bf16 v[98:101], v[182:185], v[206:209], v[98:101]
	v_mfma_f32_16x16x32_bf16 v[102:105], v[158:161], v[202:205], v[102:105]
	v_mfma_f32_16x16x32_bf16 v[102:105], v[174:177], v[206:209], v[102:105]
	v_mfma_f32_16x16x32_bf16 v[86:89], v[158:161], v[224:227], v[86:89]
	v_mfma_f32_16x16x32_bf16 v[86:89], v[174:177], v[228:231], v[86:89]
	v_mfma_f32_16x16x32_bf16 v[82:85], v[178:181], v[224:227], v[82:85]
	v_mfma_f32_16x16x32_bf16 v[82:85], v[182:185], v[228:231], v[82:85]
	v_mfma_f32_16x16x32_bf16 v[66:69], v[178:181], v[232:235], v[66:69]
	v_mfma_f32_16x16x32_bf16 v[66:69], v[182:185], v[236:239], v[66:69]
	v_mfma_f32_16x16x32_bf16 v[70:73], v[158:161], v[232:235], v[70:73]
	v_mfma_f32_16x16x32_bf16 v[70:73], v[174:177], v[236:239], v[70:73]
	v_mfma_f32_16x16x32_bf16 v[74:77], v[138:141], v[232:235], v[74:77]
	v_mfma_f32_16x16x32_bf16 v[74:77], v[142:145], v[236:239], v[74:77]
	v_mfma_f32_16x16x32_bf16 v[90:93], v[138:141], v[224:227], v[90:93]
	v_mfma_f32_16x16x32_bf16 v[90:93], v[142:145], v[228:231], v[90:93]
	v_mfma_f32_16x16x32_bf16 v[94:97], v[130:133], v[224:227], v[94:97]
	v_mfma_f32_16x16x32_bf16 v[94:97], v[134:137], v[228:231], v[94:97]
	v_mfma_f32_16x16x32_bf16 v[78:81], v[130:133], v[232:235], v[78:81]
	v_mfma_f32_16x16x32_bf16 v[78:81], v[134:137], v[236:239], v[78:81]
	s_setprio 0
	s_barrier
	s_add_i32 s57, s57, s33
	v_lshl_add_u64 v[162:163], s[16:17], 0, v[0:1]
	s_mov_b32 m0, s57
	ds_read_b128 v[186:189], v196 offset:16384
	ds_read_b128 v[198:201], v196 offset:17408
	ds_read_b128 v[202:205], v196 offset:18432
	ds_read_b128 v[206:209], v196 offset:19456
	ds_read_b128 v[224:227], v196 offset:20480
	ds_read_b128 v[228:231], v196 offset:21504
	ds_read_b128 v[232:235], v196 offset:22528
	ds_read_b128 v[236:239], v196 offset:23552
	global_load_lds_dwordx4 v[162:163], off
	s_add_i32 m0, s57, 0x2000
	s_add_u32 s58, s16, 0x80000
	v_lshl_add_u64 v[164:165], s[16:17], 0, v[146:147]
	s_addc_u32 s59, s17, 0
	s_add_i32 s57, s60, s33
	global_load_lds_dwordx4 v[164:165], off
	s_mov_b32 m0, s57
	v_lshl_add_u64 v[168:169], s[20:21], 0, v[148:149]
	global_load_lds_dwordx4 v0, s[58:59]
	s_add_i32 m0, s57, 0x2000
	s_nop 0
	global_load_lds_dwordx4 v146, s[58:59]
	v_lshl_add_u64 v[166:167], s[20:21], 0, v[150:151]
	s_mov_b32 m0, s26
	s_nop 0
	global_load_lds_dwordx4 v[166:167], off
	s_mov_b32 m0, s27
	s_nop 0
	global_load_lds_dwordx4 v[168:169], off
	s_waitcnt vmcnt(8)
	s_waitcnt lgkmcnt(0)
	s_barrier
	s_setprio 1
	s_waitcnt lgkmcnt(0)
	v_mfma_f32_16x16x32_bf16 v[62:65], v[130:133], v[186:189], v[62:65]
	v_mfma_f32_16x16x32_bf16 v[62:65], v[134:137], v[198:201], v[62:65]
	v_mfma_f32_16x16x32_bf16 v[46:49], v[130:133], v[202:205], v[46:49]
	v_mfma_f32_16x16x32_bf16 v[46:49], v[134:137], v[206:209], v[46:49]
	v_mfma_f32_16x16x32_bf16 v[42:45], v[138:141], v[202:205], v[42:45]
	v_mfma_f32_16x16x32_bf16 v[42:45], v[142:145], v[206:209], v[42:45]
	v_mfma_f32_16x16x32_bf16 v[58:61], v[138:141], v[186:189], v[58:61]
	v_mfma_f32_16x16x32_bf16 v[58:61], v[142:145], v[198:201], v[58:61]
	v_mfma_f32_16x16x32_bf16 v[54:57], v[158:161], v[186:189], v[54:57]
	v_mfma_f32_16x16x32_bf16 v[54:57], v[174:177], v[198:201], v[54:57]
	v_mfma_f32_16x16x32_bf16 v[50:53], v[178:181], v[186:189], v[50:53]
	v_mfma_f32_16x16x32_bf16 v[50:53], v[182:185], v[198:201], v[50:53]
	v_mfma_f32_16x16x32_bf16 v[34:37], v[178:181], v[202:205], v[34:37]
	v_mfma_f32_16x16x32_bf16 v[34:37], v[182:185], v[206:209], v[34:37]
	v_mfma_f32_16x16x32_bf16 v[38:41], v[158:161], v[202:205], v[38:41]
	v_mfma_f32_16x16x32_bf16 v[38:41], v[174:177], v[206:209], v[38:41]
	v_mfma_f32_16x16x32_bf16 v[22:25], v[158:161], v[224:227], v[22:25]
	v_mfma_f32_16x16x32_bf16 v[22:25], v[174:177], v[228:231], v[22:25]
	v_mfma_f32_16x16x32_bf16 v[18:21], v[178:181], v[224:227], v[18:21]
	v_mfma_f32_16x16x32_bf16 v[18:21], v[182:185], v[228:231], v[18:21]
	v_mfma_f32_16x16x32_bf16 v[2:5], v[178:181], v[232:235], v[2:5]
	v_mfma_f32_16x16x32_bf16 v[2:5], v[182:185], v[236:239], v[2:5]
	v_mfma_f32_16x16x32_bf16 v[6:9], v[158:161], v[232:235], v[6:9]
	v_mfma_f32_16x16x32_bf16 v[6:9], v[174:177], v[236:239], v[6:9]
	v_mfma_f32_16x16x32_bf16 v[10:13], v[138:141], v[232:235], v[10:13]
	v_mfma_f32_16x16x32_bf16 v[10:13], v[142:145], v[236:239], v[10:13]
	v_mfma_f32_16x16x32_bf16 v[26:29], v[138:141], v[224:227], v[26:29]
	v_mfma_f32_16x16x32_bf16 v[26:29], v[142:145], v[228:231], v[26:29]
	v_mfma_f32_16x16x32_bf16 v[30:33], v[130:133], v[224:227], v[30:33]
	v_mfma_f32_16x16x32_bf16 v[30:33], v[134:137], v[228:231], v[30:33]
	v_mfma_f32_16x16x32_bf16 v[14:17], v[130:133], v[232:235], v[14:17]
	v_mfma_f32_16x16x32_bf16 v[14:17], v[134:137], v[236:239], v[14:17]
	s_setprio 0
	s_barrier
	s_add_i32 s57, 0, 0x18000
	s_add_i32 s58, 0, 0x1c000
	v_add_u32_e32 v142, s57, v193
	v_add_u32_e32 v170, s58, v193
	ds_read_b128 v[130:133], v142
	ds_read_b128 v[134:137], v142 offset:1024
	ds_read_b128 v[138:141], v142 offset:2048
	ds_read_b128 v[142:145], v142 offset:3072
	ds_read_b128 v[158:161], v170
	ds_read_b128 v[174:177], v170 offset:1024
	ds_read_b128 v[178:181], v170 offset:2048
	ds_read_b128 v[182:185], v170 offset:3072
	s_add_u32 s20, s20, 0x80000
	s_addc_u32 s21, s21, 0
	s_mov_b32 m0, s28
	ds_read_b128 v[186:189], v196 offset:32768
	ds_read_b128 v[198:201], v196 offset:33792
	ds_read_b128 v[202:205], v196 offset:34816
	ds_read_b128 v[206:209], v196 offset:35840
	ds_read_b128 v[224:227], v196 offset:36864
	ds_read_b128 v[228:231], v196 offset:37888
	ds_read_b128 v[232:235], v196 offset:38912
	ds_read_b128 v[236:239], v196 offset:39936
	global_load_lds_dwordx4 v150, s[20:21]
	s_mov_b32 m0, s29
	s_nop 0
	global_load_lds_dwordx4 v148, s[20:21]
	s_waitcnt vmcnt(8)
	s_waitcnt lgkmcnt(0)
	s_barrier
	s_setprio 1
	s_waitcnt lgkmcnt(0)
	v_mfma_f32_16x16x32_bf16 v[126:129], v[130:133], v[186:189], v[126:129]
	v_mfma_f32_16x16x32_bf16 v[126:129], v[134:137], v[198:201], v[126:129]
	v_mfma_f32_16x16x32_bf16 v[110:113], v[130:133], v[202:205], v[110:113]
	v_mfma_f32_16x16x32_bf16 v[110:113], v[134:137], v[206:209], v[110:113]
	v_mfma_f32_16x16x32_bf16 v[106:109], v[138:141], v[202:205], v[106:109]
	v_mfma_f32_16x16x32_bf16 v[106:109], v[142:145], v[206:209], v[106:109]
	v_mfma_f32_16x16x32_bf16 v[122:125], v[138:141], v[186:189], v[122:125]
	v_mfma_f32_16x16x32_bf16 v[122:125], v[142:145], v[198:201], v[122:125]
	v_mfma_f32_16x16x32_bf16 v[118:121], v[158:161], v[186:189], v[118:121]
	v_mfma_f32_16x16x32_bf16 v[118:121], v[174:177], v[198:201], v[118:121]
	v_mfma_f32_16x16x32_bf16 v[114:117], v[178:181], v[186:189], v[114:117]
	v_mfma_f32_16x16x32_bf16 v[114:117], v[182:185], v[198:201], v[114:117]
	v_mfma_f32_16x16x32_bf16 v[98:101], v[178:181], v[202:205], v[98:101]
	v_mfma_f32_16x16x32_bf16 v[98:101], v[182:185], v[206:209], v[98:101]
	v_mfma_f32_16x16x32_bf16 v[102:105], v[158:161], v[202:205], v[102:105]
	v_mfma_f32_16x16x32_bf16 v[102:105], v[174:177], v[206:209], v[102:105]
	v_mfma_f32_16x16x32_bf16 v[86:89], v[158:161], v[224:227], v[86:89]
	v_mfma_f32_16x16x32_bf16 v[86:89], v[174:177], v[228:231], v[86:89]
	v_mfma_f32_16x16x32_bf16 v[82:85], v[178:181], v[224:227], v[82:85]
	v_mfma_f32_16x16x32_bf16 v[82:85], v[182:185], v[228:231], v[82:85]
	v_mfma_f32_16x16x32_bf16 v[66:69], v[178:181], v[232:235], v[66:69]
	v_mfma_f32_16x16x32_bf16 v[66:69], v[182:185], v[236:239], v[66:69]
	v_mfma_f32_16x16x32_bf16 v[70:73], v[158:161], v[232:235], v[70:73]
	v_mfma_f32_16x16x32_bf16 v[70:73], v[174:177], v[236:239], v[70:73]
	v_mfma_f32_16x16x32_bf16 v[74:77], v[138:141], v[232:235], v[74:77]
	v_mfma_f32_16x16x32_bf16 v[74:77], v[142:145], v[236:239], v[74:77]
	v_mfma_f32_16x16x32_bf16 v[90:93], v[138:141], v[224:227], v[90:93]
	v_mfma_f32_16x16x32_bf16 v[90:93], v[142:145], v[228:231], v[90:93]
	v_mfma_f32_16x16x32_bf16 v[94:97], v[130:133], v[224:227], v[94:97]
	v_mfma_f32_16x16x32_bf16 v[94:97], v[134:137], v[228:231], v[94:97]
	v_mfma_f32_16x16x32_bf16 v[78:81], v[130:133], v[232:235], v[78:81]
	v_mfma_f32_16x16x32_bf16 v[78:81], v[134:137], v[236:239], v[78:81]
	s_setprio 0
	s_barrier
	s_add_i32 s20, s57, s33
	v_lshl_add_u64 v[162:163], v[162:163], 0, s[30:31]
	s_mov_b32 m0, s20
	ds_read_b128 v[186:189], v196 offset:49152
	ds_read_b128 v[198:201], v196 offset:50176
	ds_read_b128 v[202:205], v196 offset:51200
	ds_read_b128 v[206:209], v196 offset:52224
	ds_read_b128 v[224:227], v196 offset:53248
	ds_read_b128 v[228:231], v196 offset:54272
	ds_read_b128 v[232:235], v196 offset:55296
	ds_read_b128 v[236:239], v196 offset:56320
	global_load_lds_dwordx4 v[162:163], off
	s_add_i32 m0, s20, 0x2000
	s_add_u32 s16, s16, 0x80080
	v_lshl_add_u64 v[162:163], v[164:165], 0, s[30:31]
	s_addc_u32 s17, s17, 0
	s_add_i32 s20, s58, s33
	global_load_lds_dwordx4 v[162:163], off
	s_mov_b32 m0, s20
	s_nop 0
	global_load_lds_dwordx4 v0, s[16:17]
	s_add_i32 m0, s20, 0x2000
	s_nop 0
	global_load_lds_dwordx4 v146, s[16:17]
	v_lshl_add_u64 v[162:163], v[166:167], 0, s[30:31]
	s_mov_b32 m0, s48
	s_nop 0
	global_load_lds_dwordx4 v[162:163], off
	v_lshl_add_u64 v[162:163], v[168:169], 0, s[30:31]
	s_mov_b32 m0, s49
	s_nop 0
	global_load_lds_dwordx4 v[162:163], off
	s_waitcnt vmcnt(8)
	s_waitcnt lgkmcnt(0)
	s_barrier
	s_setprio 1
	s_waitcnt lgkmcnt(0)
	v_mfma_f32_16x16x32_bf16 v[62:65], v[130:133], v[186:189], v[62:65]
	v_mfma_f32_16x16x32_bf16 v[62:65], v[134:137], v[198:201], v[62:65]
	v_mfma_f32_16x16x32_bf16 v[46:49], v[130:133], v[202:205], v[46:49]
	v_mfma_f32_16x16x32_bf16 v[46:49], v[134:137], v[206:209], v[46:49]
	v_mfma_f32_16x16x32_bf16 v[42:45], v[138:141], v[202:205], v[42:45]
	v_mfma_f32_16x16x32_bf16 v[42:45], v[142:145], v[206:209], v[42:45]
	v_mfma_f32_16x16x32_bf16 v[58:61], v[138:141], v[186:189], v[58:61]
	v_mfma_f32_16x16x32_bf16 v[58:61], v[142:145], v[198:201], v[58:61]
	v_mfma_f32_16x16x32_bf16 v[54:57], v[158:161], v[186:189], v[54:57]
	v_mfma_f32_16x16x32_bf16 v[54:57], v[174:177], v[198:201], v[54:57]
	v_mfma_f32_16x16x32_bf16 v[50:53], v[178:181], v[186:189], v[50:53]
	v_mfma_f32_16x16x32_bf16 v[50:53], v[182:185], v[198:201], v[50:53]
	v_mfma_f32_16x16x32_bf16 v[34:37], v[178:181], v[202:205], v[34:37]
	v_mfma_f32_16x16x32_bf16 v[34:37], v[182:185], v[206:209], v[34:37]
	v_mfma_f32_16x16x32_bf16 v[38:41], v[158:161], v[202:205], v[38:41]
	v_mfma_f32_16x16x32_bf16 v[38:41], v[174:177], v[206:209], v[38:41]
	v_mfma_f32_16x16x32_bf16 v[22:25], v[158:161], v[224:227], v[22:25]
	v_mfma_f32_16x16x32_bf16 v[22:25], v[174:177], v[228:231], v[22:25]
	v_mfma_f32_16x16x32_bf16 v[18:21], v[178:181], v[224:227], v[18:21]
	v_mfma_f32_16x16x32_bf16 v[18:21], v[182:185], v[228:231], v[18:21]
	v_mfma_f32_16x16x32_bf16 v[2:5], v[178:181], v[232:235], v[2:5]
	v_mfma_f32_16x16x32_bf16 v[2:5], v[182:185], v[236:239], v[2:5]
	v_mfma_f32_16x16x32_bf16 v[6:9], v[158:161], v[232:235], v[6:9]
	v_mfma_f32_16x16x32_bf16 v[6:9], v[174:177], v[236:239], v[6:9]
	v_mfma_f32_16x16x32_bf16 v[10:13], v[138:141], v[232:235], v[10:13]
	v_mfma_f32_16x16x32_bf16 v[10:13], v[142:145], v[236:239], v[10:13]
	v_mfma_f32_16x16x32_bf16 v[26:29], v[138:141], v[224:227], v[26:29]
	v_mfma_f32_16x16x32_bf16 v[26:29], v[142:145], v[228:231], v[26:29]
	v_mfma_f32_16x16x32_bf16 v[30:33], v[130:133], v[224:227], v[30:33]
	v_mfma_f32_16x16x32_bf16 v[30:33], v[134:137], v[228:231], v[30:33]
	v_mfma_f32_16x16x32_bf16 v[14:17], v[130:133], v[232:235], v[14:17]
	v_mfma_f32_16x16x32_bf16 v[14:17], v[134:137], v[236:239], v[14:17]
	s_setprio 0
	s_barrier
	s_add_i32 s56, s56, 2
	s_add_u32 s6, s6, 0x100
	s_addc_u32 s7, s7, 0
	s_add_u32 s54, s54, 0x100
	s_addc_u32 s55, s55, 0
	s_cmp_gt_u32 s56, 29
	s_cbranch_scc0 .LBB0_665
	v_readlane_b32 s6, v253, 2
	v_readlane_b32 s7, v253, 3
	s_and_b64 vcc, exec, s[6:7]
	s_cbranch_vccz .LBB0_670
	s_barrier
	s_cmp_lt_i32 s51, 22
	s_mov_b64 s[6:7], -1
	s_cbranch_scc1 .LBB0_671

.LBB0_1913:
	s_add_i32 s52, s20, 2
	s_add_u32 s14, s16, 0xfff80080
	s_addc_u32 s15, s17, -1
	s_add_i32 s53, 0, 0x10000
	s_cmp_eq_u32 s49, s20
	s_cselect_b32 s21, s7, s15
	s_cselect_b32 s20, s6, s14
	v_add_u32_e32 v0, s53, v189
	s_cselect_b32 s15, s13, s51
	s_cselect_b32 s14, s12, s50
	s_add_i32 s56, 0, 0x14000
	ds_read_b128 v[132:135], v0
	ds_read_b128 v[148:151], v0 offset:1024
	ds_read_b128 v[152:155], v0 offset:2048
	ds_read_b128 v[156:159], v0 offset:3072
	v_add_u32_e32 v0, s56, v189
	ds_read_b128 v[160:163], v0
	ds_read_b128 v[164:167], v0 offset:1024
	ds_read_b128 v[168:171], v0 offset:2048
	ds_read_b128 v[172:175], v0 offset:3072
	s_add_i32 m0, s26, 0xc000
	ds_read_b128 v[176:179], v191
	ds_read_b128 v[180:183], v191 offset:1024
	ds_read_b128 v[184:187], v191 offset:2048
	ds_read_b128 v[192:195], v191 offset:3072
	ds_read_b128 v[196:199], v191 offset:4096
	ds_read_b128 v[200:203], v191 offset:5120
	ds_read_b128 v[204:207], v191 offset:6144
	ds_read_b128 v[208:211], v191 offset:7168
	global_load_lds_dwordx4 v144, s[16:17]
	s_add_i32 m0, s26, 0xe000
	s_nop 0
	global_load_lds_dwordx4 v146, s[16:17]
	s_waitcnt vmcnt(8)
	s_waitcnt lgkmcnt(0)
	s_barrier
	s_setprio 1
	s_waitcnt lgkmcnt(0)
	v_mfma_f32_16x16x32_bf16 v[128:131], v[132:135], v[176:179], v[128:131]
	v_mfma_f32_16x16x32_bf16 v[128:131], v[148:151], v[180:183], v[128:131]
	v_mfma_f32_16x16x32_bf16 v[120:123], v[132:135], v[184:187], v[120:123]
	v_mfma_f32_16x16x32_bf16 v[120:123], v[148:151], v[192:195], v[120:123]
	v_mfma_f32_16x16x32_bf16 v[116:119], v[152:155], v[184:187], v[116:119]
	v_mfma_f32_16x16x32_bf16 v[116:119], v[156:159], v[192:195], v[116:119]
	v_mfma_f32_16x16x32_bf16 v[124:127], v[152:155], v[176:179], v[124:127]
	v_mfma_f32_16x16x32_bf16 v[124:127], v[156:159], v[180:183], v[124:127]
	v_mfma_f32_16x16x32_bf16 v[96:99], v[160:163], v[176:179], v[96:99]
	v_mfma_f32_16x16x32_bf16 v[96:99], v[164:167], v[180:183], v[96:99]
	v_mfma_f32_16x16x32_bf16 v[92:95], v[168:171], v[176:179], v[92:95]
	v_mfma_f32_16x16x32_bf16 v[92:95], v[172:175], v[180:183], v[92:95]
	v_mfma_f32_16x16x32_bf16 v[84:87], v[168:171], v[184:187], v[84:87]
	v_mfma_f32_16x16x32_bf16 v[84:87], v[172:175], v[192:195], v[84:87]
	v_mfma_f32_16x16x32_bf16 v[88:91], v[160:163], v[184:187], v[88:91]
	v_mfma_f32_16x16x32_bf16 v[88:91], v[164:167], v[192:195], v[88:91]
	v_mfma_f32_16x16x32_bf16 v[80:83], v[160:163], v[196:199], v[80:83]
	v_mfma_f32_16x16x32_bf16 v[80:83], v[164:167], v[200:203], v[80:83]
	v_mfma_f32_16x16x32_bf16 v[76:79], v[168:171], v[196:199], v[76:79]
	v_mfma_f32_16x16x32_bf16 v[76:79], v[172:175], v[200:203], v[76:79]
	v_mfma_f32_16x16x32_bf16 v[68:71], v[168:171], v[204:207], v[68:71]
	v_mfma_f32_16x16x32_bf16 v[68:71], v[172:175], v[208:211], v[68:71]
	v_mfma_f32_16x16x32_bf16 v[72:75], v[160:163], v[204:207], v[72:75]
	v_mfma_f32_16x16x32_bf16 v[72:75], v[164:167], v[208:211], v[72:75]
	v_mfma_f32_16x16x32_bf16 v[100:103], v[152:155], v[204:207], v[100:103]
	v_mfma_f32_16x16x32_bf16 v[100:103], v[156:159], v[208:211], v[100:103]
	v_mfma_f32_16x16x32_bf16 v[108:111], v[152:155], v[196:199], v[108:111]
	v_mfma_f32_16x16x32_bf16 v[108:111], v[156:159], v[200:203], v[108:111]
	v_mfma_f32_16x16x32_bf16 v[112:115], v[132:135], v[196:199], v[112:115]
	v_mfma_f32_16x16x32_bf16 v[112:115], v[148:151], v[200:203], v[112:115]
	v_mfma_f32_16x16x32_bf16 v[104:107], v[132:135], v[204:207], v[104:107]
	v_mfma_f32_16x16x32_bf16 v[104:107], v[148:151], v[208:211], v[104:107]
	s_setprio 0
	s_barrier
	s_add_i32 s53, s53, s33
	v_lshl_add_u64 v[212:213], s[14:15], 0, v[140:141]
	s_mov_b32 m0, s53
	ds_read_b128 v[176:179], v191 offset:16384
	ds_read_b128 v[180:183], v191 offset:17408
	ds_read_b128 v[184:187], v191 offset:18432
	ds_read_b128 v[192:195], v191 offset:19456
	ds_read_b128 v[196:199], v191 offset:20480
	ds_read_b128 v[200:203], v191 offset:21504
	ds_read_b128 v[204:207], v191 offset:22528
	ds_read_b128 v[208:211], v191 offset:23552
	global_load_lds_dwordx4 v[212:213], off
	s_add_i32 m0, s53, 0x2000
	s_add_u32 s54, s14, 0x80000
	v_lshl_add_u64 v[220:221], s[14:15], 0, v[136:137]
	s_addc_u32 s55, s15, 0
	s_add_i32 s53, s56, s33
	global_load_lds_dwordx4 v[220:221], off
	s_mov_b32 m0, s53
	v_lshl_add_u64 v[224:225], s[20:21], 0, v[142:143]
	global_load_lds_dwordx4 v140, s[54:55]
	s_add_i32 m0, s53, 0x2000
	v_lshl_add_u64 v[226:227], s[20:21], 0, v[138:139]
	global_load_lds_dwordx4 v136, s[54:55]
	s_mov_b32 m0, s26
	s_nop 0
	global_load_lds_dwordx4 v[224:225], off
	s_mov_b32 m0, s27
	s_nop 0
	global_load_lds_dwordx4 v[226:227], off
	s_waitcnt vmcnt(8)
	s_waitcnt lgkmcnt(0)
	s_barrier
	s_setprio 1
	s_waitcnt lgkmcnt(0)
	v_mfma_f32_16x16x32_bf16 v[64:67], v[132:135], v[176:179], v[64:67]
	v_mfma_f32_16x16x32_bf16 v[64:67], v[148:151], v[180:183], v[64:67]
	v_mfma_f32_16x16x32_bf16 v[56:59], v[132:135], v[184:187], v[56:59]
	v_mfma_f32_16x16x32_bf16 v[56:59], v[148:151], v[192:195], v[56:59]
	v_mfma_f32_16x16x32_bf16 v[52:55], v[152:155], v[184:187], v[52:55]
	v_mfma_f32_16x16x32_bf16 v[52:55], v[156:159], v[192:195], v[52:55]
	v_mfma_f32_16x16x32_bf16 v[60:63], v[152:155], v[176:179], v[60:63]
	v_mfma_f32_16x16x32_bf16 v[60:63], v[156:159], v[180:183], v[60:63]
	v_mfma_f32_16x16x32_bf16 v[32:35], v[160:163], v[176:179], v[32:35]
	v_mfma_f32_16x16x32_bf16 v[32:35], v[164:167], v[180:183], v[32:35]
	v_mfma_f32_16x16x32_bf16 v[28:31], v[168:171], v[176:179], v[28:31]
	v_mfma_f32_16x16x32_bf16 v[28:31], v[172:175], v[180:183], v[28:31]
	v_mfma_f32_16x16x32_bf16 v[20:23], v[168:171], v[184:187], v[20:23]
	v_mfma_f32_16x16x32_bf16 v[20:23], v[172:175], v[192:195], v[20:23]
	v_mfma_f32_16x16x32_bf16 v[24:27], v[160:163], v[184:187], v[24:27]
	v_mfma_f32_16x16x32_bf16 v[24:27], v[164:167], v[192:195], v[24:27]
	v_mfma_f32_16x16x32_bf16 v[16:19], v[160:163], v[196:199], v[16:19]
	v_mfma_f32_16x16x32_bf16 v[16:19], v[164:167], v[200:203], v[16:19]
	v_mfma_f32_16x16x32_bf16 v[12:15], v[168:171], v[196:199], v[12:15]
	v_mfma_f32_16x16x32_bf16 v[12:15], v[172:175], v[200:203], v[12:15]
	v_mfma_f32_16x16x32_bf16 v[2:5], v[168:171], v[204:207], v[4:7]
	v_mfma_f32_16x16x32_bf16 v[2:5], v[172:175], v[208:211], v[2:5]
	v_mfma_f32_16x16x32_bf16 v[8:11], v[160:163], v[204:207], v[8:11]
	v_mfma_f32_16x16x32_bf16 v[8:11], v[164:167], v[208:211], v[8:11]
	v_mfma_f32_16x16x32_bf16 v[36:39], v[152:155], v[204:207], v[36:39]
	v_mfma_f32_16x16x32_bf16 v[36:39], v[156:159], v[208:211], v[36:39]
	v_mfma_f32_16x16x32_bf16 v[44:47], v[152:155], v[196:199], v[44:47]
	v_mfma_f32_16x16x32_bf16 v[44:47], v[156:159], v[200:203], v[44:47]
	v_mfma_f32_16x16x32_bf16 v[48:51], v[132:135], v[196:199], v[48:51]
	v_mfma_f32_16x16x32_bf16 v[48:51], v[148:151], v[200:203], v[48:51]
	v_mfma_f32_16x16x32_bf16 v[40:43], v[132:135], v[204:207], v[40:43]
	v_mfma_f32_16x16x32_bf16 v[40:43], v[148:151], v[208:211], v[40:43]
	s_setprio 0
	s_barrier
	s_add_i32 s53, 0, 0x18000
	v_add_u32_e32 v0, s53, v189
	s_add_i32 s54, 0, 0x1c000
	ds_read_b128 v[132:135], v0
	ds_read_b128 v[148:151], v0 offset:1024
	ds_read_b128 v[152:155], v0 offset:2048
	ds_read_b128 v[156:159], v0 offset:3072
	v_add_u32_e32 v0, s54, v189
	ds_read_b128 v[160:163], v0
	ds_read_b128 v[164:167], v0 offset:1024
	ds_read_b128 v[168:171], v0 offset:2048
	ds_read_b128 v[172:175], v0 offset:3072
	s_add_u32 s20, s20, 0x80000
	s_addc_u32 s21, s21, 0
	s_mov_b32 m0, s28
	ds_read_b128 v[176:179], v191 offset:32768
	ds_read_b128 v[180:183], v191 offset:33792
	ds_read_b128 v[184:187], v191 offset:34816
	ds_read_b128 v[192:195], v191 offset:35840
	ds_read_b128 v[196:199], v191 offset:36864
	ds_read_b128 v[200:203], v191 offset:37888
	ds_read_b128 v[204:207], v191 offset:38912
	ds_read_b128 v[208:211], v191 offset:39936
	global_load_lds_dwordx4 v142, s[20:21]
	s_mov_b32 m0, s29
	s_nop 0
	global_load_lds_dwordx4 v138, s[20:21]
	s_waitcnt vmcnt(8)
	s_waitcnt lgkmcnt(0)
	s_barrier
	s_setprio 1
	s_waitcnt lgkmcnt(0)
	v_mfma_f32_16x16x32_bf16 v[128:131], v[132:135], v[176:179], v[128:131]
	v_mfma_f32_16x16x32_bf16 v[128:131], v[148:151], v[180:183], v[128:131]
	v_mfma_f32_16x16x32_bf16 v[120:123], v[132:135], v[184:187], v[120:123]
	v_mfma_f32_16x16x32_bf16 v[120:123], v[148:151], v[192:195], v[120:123]
	v_mfma_f32_16x16x32_bf16 v[116:119], v[152:155], v[184:187], v[116:119]
	v_mfma_f32_16x16x32_bf16 v[116:119], v[156:159], v[192:195], v[116:119]
	v_mfma_f32_16x16x32_bf16 v[124:127], v[152:155], v[176:179], v[124:127]
	v_mfma_f32_16x16x32_bf16 v[124:127], v[156:159], v[180:183], v[124:127]
	v_mfma_f32_16x16x32_bf16 v[96:99], v[160:163], v[176:179], v[96:99]
	v_mfma_f32_16x16x32_bf16 v[96:99], v[164:167], v[180:183], v[96:99]
	v_mfma_f32_16x16x32_bf16 v[92:95], v[168:171], v[176:179], v[92:95]
	v_mfma_f32_16x16x32_bf16 v[92:95], v[172:175], v[180:183], v[92:95]
	v_mfma_f32_16x16x32_bf16 v[84:87], v[168:171], v[184:187], v[84:87]
	v_mfma_f32_16x16x32_bf16 v[84:87], v[172:175], v[192:195], v[84:87]
	v_mfma_f32_16x16x32_bf16 v[88:91], v[160:163], v[184:187], v[88:91]
	v_mfma_f32_16x16x32_bf16 v[88:91], v[164:167], v[192:195], v[88:91]
	v_mfma_f32_16x16x32_bf16 v[80:83], v[160:163], v[196:199], v[80:83]
	v_mfma_f32_16x16x32_bf16 v[80:83], v[164:167], v[200:203], v[80:83]
	v_mfma_f32_16x16x32_bf16 v[76:79], v[168:171], v[196:199], v[76:79]
	v_mfma_f32_16x16x32_bf16 v[76:79], v[172:175], v[200:203], v[76:79]
	v_mfma_f32_16x16x32_bf16 v[68:71], v[168:171], v[204:207], v[68:71]
	v_mfma_f32_16x16x32_bf16 v[68:71], v[172:175], v[208:211], v[68:71]
	v_mfma_f32_16x16x32_bf16 v[72:75], v[160:163], v[204:207], v[72:75]
	v_mfma_f32_16x16x32_bf16 v[72:75], v[164:167], v[208:211], v[72:75]
	v_mfma_f32_16x16x32_bf16 v[100:103], v[152:155], v[204:207], v[100:103]
	v_mfma_f32_16x16x32_bf16 v[100:103], v[156:159], v[208:211], v[100:103]
	v_mfma_f32_16x16x32_bf16 v[108:111], v[152:155], v[196:199], v[108:111]
	v_mfma_f32_16x16x32_bf16 v[108:111], v[156:159], v[200:203], v[108:111]
	v_mfma_f32_16x16x32_bf16 v[112:115], v[132:135], v[196:199], v[112:115]
	v_mfma_f32_16x16x32_bf16 v[112:115], v[148:151], v[200:203], v[112:115]
	v_mfma_f32_16x16x32_bf16 v[104:107], v[132:135], v[204:207], v[104:107]
	v_mfma_f32_16x16x32_bf16 v[104:107], v[148:151], v[208:211], v[104:107]
	s_setprio 0
	s_barrier
	s_add_i32 s20, s53, s33
	v_lshl_add_u64 v[6:7], v[212:213], 0, s[30:31]
	s_mov_b32 m0, s20
	ds_read_b128 v[176:179], v191 offset:49152
	ds_read_b128 v[180:183], v191 offset:50176
	ds_read_b128 v[184:187], v191 offset:51200
	ds_read_b128 v[192:195], v191 offset:52224
	ds_read_b128 v[196:199], v191 offset:53248
	ds_read_b128 v[200:203], v191 offset:54272
	ds_read_b128 v[204:207], v191 offset:55296
	ds_read_b128 v[208:211], v191 offset:56320
	global_load_lds_dwordx4 v[6:7], off
	s_add_i32 m0, s20, 0x2000
	s_add_u32 s14, s14, 0x80080
	v_lshl_add_u64 v[6:7], v[220:221], 0, s[30:31]
	s_addc_u32 s15, s15, 0
	s_add_i32 s20, s54, s33
	global_load_lds_dwordx4 v[6:7], off
	s_mov_b32 m0, s20
	s_nop 0
	global_load_lds_dwordx4 v140, s[14:15]
	s_add_i32 m0, s20, 0x2000
	s_nop 0
	global_load_lds_dwordx4 v136, s[14:15]
	v_lshl_add_u64 v[6:7], v[224:225], 0, s[30:31]
	s_mov_b32 m0, s34
	s_nop 0
	global_load_lds_dwordx4 v[6:7], off
	v_lshl_add_u64 v[6:7], v[226:227], 0, s[30:31]
	s_mov_b32 m0, s35
	s_nop 0
	global_load_lds_dwordx4 v[6:7], off
	s_waitcnt vmcnt(8)
	s_waitcnt lgkmcnt(0)
	s_barrier
	s_setprio 1
	s_waitcnt lgkmcnt(0)
	v_mfma_f32_16x16x32_bf16 v[64:67], v[132:135], v[176:179], v[64:67]
	v_mfma_f32_16x16x32_bf16 v[64:67], v[148:151], v[180:183], v[64:67]
	v_mfma_f32_16x16x32_bf16 v[56:59], v[132:135], v[184:187], v[56:59]
	v_mfma_f32_16x16x32_bf16 v[56:59], v[148:151], v[192:195], v[56:59]
	v_mfma_f32_16x16x32_bf16 v[52:55], v[152:155], v[184:187], v[52:55]
	v_mfma_f32_16x16x32_bf16 v[52:55], v[156:159], v[192:195], v[52:55]
	v_mfma_f32_16x16x32_bf16 v[60:63], v[152:155], v[176:179], v[60:63]
	v_mfma_f32_16x16x32_bf16 v[60:63], v[156:159], v[180:183], v[60:63]
	v_mfma_f32_16x16x32_bf16 v[32:35], v[160:163], v[176:179], v[32:35]
	v_mfma_f32_16x16x32_bf16 v[32:35], v[164:167], v[180:183], v[32:35]
	v_mfma_f32_16x16x32_bf16 v[28:31], v[168:171], v[176:179], v[28:31]
	v_mfma_f32_16x16x32_bf16 v[28:31], v[172:175], v[180:183], v[28:31]
	v_mfma_f32_16x16x32_bf16 v[20:23], v[168:171], v[184:187], v[20:23]
	v_mfma_f32_16x16x32_bf16 v[20:23], v[172:175], v[192:195], v[20:23]
	v_mfma_f32_16x16x32_bf16 v[24:27], v[160:163], v[184:187], v[24:27]
	v_mfma_f32_16x16x32_bf16 v[24:27], v[164:167], v[192:195], v[24:27]
	v_mfma_f32_16x16x32_bf16 v[16:19], v[160:163], v[196:199], v[16:19]
	v_mfma_f32_16x16x32_bf16 v[16:19], v[164:167], v[200:203], v[16:19]
	v_mfma_f32_16x16x32_bf16 v[12:15], v[168:171], v[196:199], v[12:15]
	v_mfma_f32_16x16x32_bf16 v[12:15], v[172:175], v[200:203], v[12:15]
	v_mfma_f32_16x16x32_bf16 v[6:9], v[160:163], v[204:207], v[8:11]
	v_mfma_f32_16x16x32_bf16 v[8:11], v[164:167], v[208:211], v[6:9]
	v_mfma_f32_16x16x32_bf16 v[2:5], v[168:171], v[204:207], v[2:5]
	v_mfma_f32_16x16x32_bf16 v[4:7], v[172:175], v[208:211], v[2:5]
	v_mfma_f32_16x16x32_bf16 v[36:39], v[152:155], v[204:207], v[36:39]
	v_mfma_f32_16x16x32_bf16 v[36:39], v[156:159], v[208:211], v[36:39]
	v_mfma_f32_16x16x32_bf16 v[44:47], v[152:155], v[196:199], v[44:47]
	v_mfma_f32_16x16x32_bf16 v[44:47], v[156:159], v[200:203], v[44:47]
	v_mfma_f32_16x16x32_bf16 v[48:51], v[132:135], v[196:199], v[48:51]
	v_mfma_f32_16x16x32_bf16 v[48:51], v[148:151], v[200:203], v[48:51]
	v_mfma_f32_16x16x32_bf16 v[40:43], v[132:135], v[204:207], v[40:43]
	v_mfma_f32_16x16x32_bf16 v[40:43], v[148:151], v[208:211], v[40:43]
	s_setprio 0
	s_barrier
	s_add_u32 s16, s16, 0x100
	s_addc_u32 s17, s17, 0
	s_add_u32 s50, s50, 0x100
	s_addc_u32 s51, s51, 0
	s_cmp_ge_u32 s52, s11
	s_mov_b32 s20, s52
	s_cbranch_scc0 .LBB0_1913
	v_readlane_b32 s14, v253, 2
	v_readlane_b32 s15, v253, 3
	s_and_b64 vcc, exec, s[14:15]
	s_cbranch_vccz .LBB0_1916
	s_barrier

.LBB0_1997:
	s_add_u32 s22, s16, 0xfff80080
	s_addc_u32 s23, s17, -1
	s_add_i32 s69, 0, 0x10000
	s_cmp_eq_u32 s25, 28
	s_cselect_b32 s27, s11, s23
	s_cselect_b32 s26, s18, s22
	s_cselect_b32 s23, s9, s24
	s_cselect_b32 s22, s19, s21
	s_add_i32 s72, 0, 0x14000
	v_add_u32_e32 v142, s69, v205
	v_add_u32_e32 v162, s72, v205
	ds_read_b128 v[130:133], v142
	ds_read_b128 v[134:137], v142 offset:1024
	ds_read_b128 v[138:141], v142 offset:2048
	ds_read_b128 v[142:145], v142 offset:3072
	ds_read_b128 v[146:149], v162
	ds_read_b128 v[150:153], v162 offset:1024
	ds_read_b128 v[154:157], v162 offset:2048
	ds_read_b128 v[162:165], v162 offset:3072
	s_add_i32 m0, s54, 0xc000
	ds_read_b128 v[166:169], v230
	ds_read_b128 v[170:173], v230 offset:1024
	ds_read_b128 v[184:187], v230 offset:2048
	ds_read_b128 v[188:191], v230 offset:3072
	ds_read_b128 v[192:195], v230 offset:4096
	ds_read_b128 v[196:199], v230 offset:5120
	ds_read_b128 v[200:203], v230 offset:6144
	ds_read_b128 v[232:235], v230 offset:7168
	global_load_lds_dwordx4 v180, s[16:17]
	s_add_i32 m0, s54, 0xe000
	s_nop 0
	global_load_lds_dwordx4 v182, s[16:17]
	s_waitcnt vmcnt(8)
	s_waitcnt lgkmcnt(0)
	s_barrier
	s_setprio 1
	s_waitcnt lgkmcnt(0)
	v_mfma_f32_16x16x32_bf16 v[126:129], v[130:133], v[166:169], v[126:129]
	v_mfma_f32_16x16x32_bf16 v[126:129], v[134:137], v[170:173], v[126:129]
	v_mfma_f32_16x16x32_bf16 v[118:121], v[130:133], v[184:187], v[118:121]
	v_mfma_f32_16x16x32_bf16 v[118:121], v[134:137], v[188:191], v[118:121]
	v_mfma_f32_16x16x32_bf16 v[86:89], v[138:141], v[184:187], v[86:89]
	v_mfma_f32_16x16x32_bf16 v[86:89], v[142:145], v[188:191], v[86:89]
	v_mfma_f32_16x16x32_bf16 v[74:77], v[138:141], v[166:169], v[74:77]
	v_mfma_f32_16x16x32_bf16 v[74:77], v[142:145], v[170:173], v[74:77]
	v_mfma_f32_16x16x32_bf16 v[122:125], v[146:149], v[166:169], v[122:125]
	v_mfma_f32_16x16x32_bf16 v[122:125], v[150:153], v[170:173], v[122:125]
	v_mfma_f32_16x16x32_bf16 v[82:85], v[154:157], v[166:169], v[82:85]
	v_mfma_f32_16x16x32_bf16 v[82:85], v[162:165], v[170:173], v[82:85]
	v_mfma_f32_16x16x32_bf16 v[90:93], v[154:157], v[184:187], v[90:93]
	v_mfma_f32_16x16x32_bf16 v[90:93], v[162:165], v[188:191], v[90:93]
	v_mfma_f32_16x16x32_bf16 v[114:117], v[146:149], v[184:187], v[114:117]
	v_mfma_f32_16x16x32_bf16 v[114:117], v[150:153], v[188:191], v[114:117]
	v_mfma_f32_16x16x32_bf16 v[106:109], v[146:149], v[192:195], v[106:109]
	v_mfma_f32_16x16x32_bf16 v[106:109], v[150:153], v[196:199], v[106:109]
	v_mfma_f32_16x16x32_bf16 v[70:73], v[154:157], v[192:195], v[70:73]
	v_mfma_f32_16x16x32_bf16 v[70:73], v[162:165], v[196:199], v[70:73]
	v_mfma_f32_16x16x32_bf16 v[42:45], v[154:157], v[200:203], v[42:45]
	v_mfma_f32_16x16x32_bf16 v[42:45], v[162:165], v[232:235], v[42:45]
	v_mfma_f32_16x16x32_bf16 v[98:101], v[146:149], v[200:203], v[98:101]
	v_mfma_f32_16x16x32_bf16 v[98:101], v[150:153], v[232:235], v[98:101]
	v_mfma_f32_16x16x32_bf16 v[38:41], v[138:141], v[200:203], v[38:41]
	v_mfma_f32_16x16x32_bf16 v[38:41], v[142:145], v[232:235], v[38:41]
	v_mfma_f32_16x16x32_bf16 v[66:69], v[138:141], v[192:195], v[66:69]
	v_mfma_f32_16x16x32_bf16 v[66:69], v[142:145], v[196:199], v[66:69]
	v_mfma_f32_16x16x32_bf16 v[110:113], v[130:133], v[192:195], v[110:113]
	v_mfma_f32_16x16x32_bf16 v[110:113], v[134:137], v[196:199], v[110:113]
	v_mfma_f32_16x16x32_bf16 v[102:105], v[130:133], v[200:203], v[102:105]
	v_mfma_f32_16x16x32_bf16 v[102:105], v[134:137], v[232:235], v[102:105]
	s_setprio 0
	s_barrier
	s_add_i32 s69, s69, s33
	v_lshl_add_u64 v[212:213], s[22:23], 0, v[0:1]
	s_mov_b32 m0, s69
	ds_read_b128 v[166:169], v230 offset:16384
	ds_read_b128 v[170:173], v230 offset:17408
	ds_read_b128 v[184:187], v230 offset:18432
	ds_read_b128 v[188:191], v230 offset:19456
	ds_read_b128 v[192:195], v230 offset:20480
	ds_read_b128 v[196:199], v230 offset:21504
	ds_read_b128 v[200:203], v230 offset:22528
	ds_read_b128 v[232:235], v230 offset:23552
	global_load_lds_dwordx4 v[212:213], off
	s_add_i32 m0, s69, 0x2000
	s_add_u32 s70, s22, 0x80000
	v_lshl_add_u64 v[220:221], s[22:23], 0, v[158:159]
	s_addc_u32 s71, s23, 0
	s_add_i32 s69, s72, s33
	global_load_lds_dwordx4 v[220:221], off
	s_mov_b32 m0, s69
	v_lshl_add_u64 v[238:239], s[26:27], 0, v[160:161]
	global_load_lds_dwordx4 v0, s[70:71]
	s_add_i32 m0, s69, 0x2000
	s_nop 0
	global_load_lds_dwordx4 v158, s[70:71]
	v_lshl_add_u64 v[236:237], s[26:27], 0, v[174:175]
	s_mov_b32 m0, s54
	s_nop 0
	global_load_lds_dwordx4 v[236:237], off
	s_mov_b32 m0, s55
	s_nop 0
	global_load_lds_dwordx4 v[238:239], off
	s_waitcnt vmcnt(8)
	s_waitcnt lgkmcnt(0)
	s_barrier
	s_setprio 1
	s_waitcnt lgkmcnt(0)
	v_mfma_f32_16x16x32_bf16 v[94:97], v[130:133], v[166:169], v[94:97]
	v_mfma_f32_16x16x32_bf16 v[94:97], v[134:137], v[170:173], v[94:97]
	v_mfma_f32_16x16x32_bf16 v[62:65], v[130:133], v[184:187], v[62:65]
	v_mfma_f32_16x16x32_bf16 v[62:65], v[134:137], v[188:191], v[62:65]
	v_mfma_f32_16x16x32_bf16 v[30:33], v[138:141], v[184:187], v[30:33]
	v_mfma_f32_16x16x32_bf16 v[30:33], v[142:145], v[188:191], v[30:33]
	v_mfma_f32_16x16x32_bf16 v[50:53], v[138:141], v[166:169], v[50:53]
	v_mfma_f32_16x16x32_bf16 v[50:53], v[142:145], v[170:173], v[50:53]
	v_mfma_f32_16x16x32_bf16 v[78:81], v[146:149], v[166:169], v[78:81]
	v_mfma_f32_16x16x32_bf16 v[78:81], v[150:153], v[170:173], v[78:81]
	v_mfma_f32_16x16x32_bf16 v[58:61], v[154:157], v[166:169], v[58:61]
	v_mfma_f32_16x16x32_bf16 v[58:61], v[162:165], v[170:173], v[58:61]
	v_mfma_f32_16x16x32_bf16 v[34:37], v[154:157], v[184:187], v[34:37]
	v_mfma_f32_16x16x32_bf16 v[34:37], v[162:165], v[188:191], v[34:37]
	v_mfma_f32_16x16x32_bf16 v[54:57], v[146:149], v[184:187], v[54:57]
	v_mfma_f32_16x16x32_bf16 v[54:57], v[150:153], v[188:191], v[54:57]
	v_mfma_f32_16x16x32_bf16 v[26:29], v[146:149], v[192:195], v[26:29]
	v_mfma_f32_16x16x32_bf16 v[26:29], v[150:153], v[196:199], v[26:29]
	v_mfma_f32_16x16x32_bf16 v[14:17], v[154:157], v[192:195], v[14:17]
	v_mfma_f32_16x16x32_bf16 v[14:17], v[162:165], v[196:199], v[14:17]
	v_mfma_f32_16x16x32_bf16 v[6:9], v[154:157], v[200:203], v[6:9]
	v_mfma_f32_16x16x32_bf16 v[6:9], v[162:165], v[232:235], v[6:9]
	v_mfma_f32_16x16x32_bf16 v[18:21], v[146:149], v[200:203], v[18:21]
	v_mfma_f32_16x16x32_bf16 v[18:21], v[150:153], v[232:235], v[18:21]
	v_mfma_f32_16x16x32_bf16 v[2:5], v[138:141], v[200:203], v[2:5]
	v_mfma_f32_16x16x32_bf16 v[2:5], v[142:145], v[232:235], v[2:5]
	v_mfma_f32_16x16x32_bf16 v[10:13], v[138:141], v[192:195], v[10:13]
	v_mfma_f32_16x16x32_bf16 v[10:13], v[142:145], v[196:199], v[10:13]
	v_mfma_f32_16x16x32_bf16 v[46:49], v[130:133], v[192:195], v[46:49]
	v_mfma_f32_16x16x32_bf16 v[46:49], v[134:137], v[196:199], v[46:49]
	v_mfma_f32_16x16x32_bf16 v[22:25], v[130:133], v[200:203], v[22:25]
	v_mfma_f32_16x16x32_bf16 v[22:25], v[134:137], v[232:235], v[22:25]
	s_setprio 0
	s_barrier
	s_add_i32 s69, 0, 0x18000
	s_add_i32 s70, 0, 0x1c000
	v_add_u32_e32 v142, s69, v205
	v_add_u32_e32 v162, s70, v205
	ds_read_b128 v[130:133], v142
	ds_read_b128 v[134:137], v142 offset:1024
	ds_read_b128 v[138:141], v142 offset:2048
	ds_read_b128 v[142:145], v142 offset:3072
	ds_read_b128 v[146:149], v162
	ds_read_b128 v[150:153], v162 offset:1024
	ds_read_b128 v[154:157], v162 offset:2048
	ds_read_b128 v[162:165], v162 offset:3072
	s_add_u32 s26, s26, 0x80000
	s_addc_u32 s27, s27, 0
	s_mov_b32 m0, s56
	ds_read_b128 v[166:169], v230 offset:32768
	ds_read_b128 v[170:173], v230 offset:33792
	ds_read_b128 v[184:187], v230 offset:34816
	ds_read_b128 v[188:191], v230 offset:35840
	ds_read_b128 v[192:195], v230 offset:36864
	ds_read_b128 v[196:199], v230 offset:37888
	ds_read_b128 v[200:203], v230 offset:38912
	ds_read_b128 v[232:235], v230 offset:39936
	global_load_lds_dwordx4 v174, s[26:27]
	s_mov_b32 m0, s57
	s_nop 0
	global_load_lds_dwordx4 v160, s[26:27]
	s_waitcnt vmcnt(8)
	s_waitcnt lgkmcnt(0)
	s_barrier
	s_setprio 1
	s_waitcnt lgkmcnt(0)
	v_mfma_f32_16x16x32_bf16 v[126:129], v[130:133], v[166:169], v[126:129]
	v_mfma_f32_16x16x32_bf16 v[126:129], v[134:137], v[170:173], v[126:129]
	v_mfma_f32_16x16x32_bf16 v[118:121], v[130:133], v[184:187], v[118:121]
	v_mfma_f32_16x16x32_bf16 v[118:121], v[134:137], v[188:191], v[118:121]
	v_mfma_f32_16x16x32_bf16 v[86:89], v[138:141], v[184:187], v[86:89]
	v_mfma_f32_16x16x32_bf16 v[86:89], v[142:145], v[188:191], v[86:89]
	v_mfma_f32_16x16x32_bf16 v[74:77], v[138:141], v[166:169], v[74:77]
	v_mfma_f32_16x16x32_bf16 v[74:77], v[142:145], v[170:173], v[74:77]
	v_mfma_f32_16x16x32_bf16 v[122:125], v[146:149], v[166:169], v[122:125]
	v_mfma_f32_16x16x32_bf16 v[122:125], v[150:153], v[170:173], v[122:125]
	v_mfma_f32_16x16x32_bf16 v[82:85], v[154:157], v[166:169], v[82:85]
	v_mfma_f32_16x16x32_bf16 v[82:85], v[162:165], v[170:173], v[82:85]
	v_mfma_f32_16x16x32_bf16 v[90:93], v[154:157], v[184:187], v[90:93]
	v_mfma_f32_16x16x32_bf16 v[90:93], v[162:165], v[188:191], v[90:93]
	v_mfma_f32_16x16x32_bf16 v[114:117], v[146:149], v[184:187], v[114:117]
	v_mfma_f32_16x16x32_bf16 v[114:117], v[150:153], v[188:191], v[114:117]
	v_mfma_f32_16x16x32_bf16 v[106:109], v[146:149], v[192:195], v[106:109]
	v_mfma_f32_16x16x32_bf16 v[106:109], v[150:153], v[196:199], v[106:109]
	v_mfma_f32_16x16x32_bf16 v[70:73], v[154:157], v[192:195], v[70:73]
	v_mfma_f32_16x16x32_bf16 v[70:73], v[162:165], v[196:199], v[70:73]
	v_mfma_f32_16x16x32_bf16 v[42:45], v[154:157], v[200:203], v[42:45]
	v_mfma_f32_16x16x32_bf16 v[42:45], v[162:165], v[232:235], v[42:45]
	v_mfma_f32_16x16x32_bf16 v[98:101], v[146:149], v[200:203], v[98:101]
	v_mfma_f32_16x16x32_bf16 v[98:101], v[150:153], v[232:235], v[98:101]
	v_mfma_f32_16x16x32_bf16 v[38:41], v[138:141], v[200:203], v[38:41]
	v_mfma_f32_16x16x32_bf16 v[38:41], v[142:145], v[232:235], v[38:41]
	v_mfma_f32_16x16x32_bf16 v[66:69], v[138:141], v[192:195], v[66:69]
	v_mfma_f32_16x16x32_bf16 v[66:69], v[142:145], v[196:199], v[66:69]
	v_mfma_f32_16x16x32_bf16 v[110:113], v[130:133], v[192:195], v[110:113]
	v_mfma_f32_16x16x32_bf16 v[110:113], v[134:137], v[196:199], v[110:113]
	v_mfma_f32_16x16x32_bf16 v[102:105], v[130:133], v[200:203], v[102:105]
	v_mfma_f32_16x16x32_bf16 v[102:105], v[134:137], v[232:235], v[102:105]
	s_setprio 0
	s_barrier
	s_add_i32 s26, s69, s33
	v_lshl_add_u64 v[212:213], v[212:213], 0, s[30:31]
	s_mov_b32 m0, s26
	ds_read_b128 v[166:169], v230 offset:49152
	ds_read_b128 v[170:173], v230 offset:50176
	ds_read_b128 v[184:187], v230 offset:51200
	ds_read_b128 v[188:191], v230 offset:52224
	ds_read_b128 v[192:195], v230 offset:53248
	ds_read_b128 v[196:199], v230 offset:54272
	ds_read_b128 v[200:203], v230 offset:55296
	ds_read_b128 v[232:235], v230 offset:56320
	global_load_lds_dwordx4 v[212:213], off
	s_add_i32 m0, s26, 0x2000
	s_add_u32 s22, s22, 0x80080
	v_lshl_add_u64 v[212:213], v[220:221], 0, s[30:31]
	s_addc_u32 s23, s23, 0
	s_add_i32 s26, s70, s33
	global_load_lds_dwordx4 v[212:213], off
	s_mov_b32 m0, s26
	s_nop 0
	global_load_lds_dwordx4 v0, s[22:23]
	s_add_i32 m0, s26, 0x2000
	s_nop 0
	global_load_lds_dwordx4 v158, s[22:23]
	v_lshl_add_u64 v[212:213], v[236:237], 0, s[30:31]
	s_mov_b32 m0, s59
	s_nop 0
	global_load_lds_dwordx4 v[212:213], off
	v_lshl_add_u64 v[212:213], v[238:239], 0, s[30:31]
	s_mov_b32 m0, s60
	s_nop 0
	global_load_lds_dwordx4 v[212:213], off
	s_waitcnt vmcnt(8)
	s_waitcnt lgkmcnt(0)
	s_barrier
	s_setprio 1
	s_waitcnt lgkmcnt(0)
	v_mfma_f32_16x16x32_bf16 v[94:97], v[130:133], v[166:169], v[94:97]
	v_mfma_f32_16x16x32_bf16 v[94:97], v[134:137], v[170:173], v[94:97]
	v_mfma_f32_16x16x32_bf16 v[62:65], v[130:133], v[184:187], v[62:65]
	v_mfma_f32_16x16x32_bf16 v[62:65], v[134:137], v[188:191], v[62:65]
	v_mfma_f32_16x16x32_bf16 v[30:33], v[138:141], v[184:187], v[30:33]
	v_mfma_f32_16x16x32_bf16 v[30:33], v[142:145], v[188:191], v[30:33]
	v_mfma_f32_16x16x32_bf16 v[50:53], v[138:141], v[166:169], v[50:53]
	v_mfma_f32_16x16x32_bf16 v[50:53], v[142:145], v[170:173], v[50:53]
	v_mfma_f32_16x16x32_bf16 v[78:81], v[146:149], v[166:169], v[78:81]
	v_mfma_f32_16x16x32_bf16 v[78:81], v[150:153], v[170:173], v[78:81]
	v_mfma_f32_16x16x32_bf16 v[58:61], v[154:157], v[166:169], v[58:61]
	v_mfma_f32_16x16x32_bf16 v[58:61], v[162:165], v[170:173], v[58:61]
	v_mfma_f32_16x16x32_bf16 v[34:37], v[154:157], v[184:187], v[34:37]
	v_mfma_f32_16x16x32_bf16 v[34:37], v[162:165], v[188:191], v[34:37]
	v_mfma_f32_16x16x32_bf16 v[54:57], v[146:149], v[184:187], v[54:57]
	v_mfma_f32_16x16x32_bf16 v[54:57], v[150:153], v[188:191], v[54:57]
	v_mfma_f32_16x16x32_bf16 v[26:29], v[146:149], v[192:195], v[26:29]
	v_mfma_f32_16x16x32_bf16 v[26:29], v[150:153], v[196:199], v[26:29]
	v_mfma_f32_16x16x32_bf16 v[14:17], v[154:157], v[192:195], v[14:17]
	v_mfma_f32_16x16x32_bf16 v[14:17], v[162:165], v[196:199], v[14:17]
	v_mfma_f32_16x16x32_bf16 v[6:9], v[154:157], v[200:203], v[6:9]
	v_mfma_f32_16x16x32_bf16 v[6:9], v[162:165], v[232:235], v[6:9]
	v_mfma_f32_16x16x32_bf16 v[18:21], v[146:149], v[200:203], v[18:21]
	v_mfma_f32_16x16x32_bf16 v[18:21], v[150:153], v[232:235], v[18:21]
	v_mfma_f32_16x16x32_bf16 v[2:5], v[138:141], v[200:203], v[2:5]
	v_mfma_f32_16x16x32_bf16 v[2:5], v[142:145], v[232:235], v[2:5]
	v_mfma_f32_16x16x32_bf16 v[10:13], v[138:141], v[192:195], v[10:13]
	v_mfma_f32_16x16x32_bf16 v[10:13], v[142:145], v[196:199], v[10:13]
	v_mfma_f32_16x16x32_bf16 v[46:49], v[130:133], v[192:195], v[46:49]
	v_mfma_f32_16x16x32_bf16 v[46:49], v[134:137], v[196:199], v[46:49]
	v_mfma_f32_16x16x32_bf16 v[22:25], v[130:133], v[200:203], v[22:25]
	v_mfma_f32_16x16x32_bf16 v[22:25], v[134:137], v[232:235], v[22:25]
	s_setprio 0
	s_barrier
	s_add_i32 s25, s25, 2
	s_add_u32 s16, s16, 0x100
	s_addc_u32 s17, s17, 0
	s_add_u32 s21, s21, 0x100
	s_addc_u32 s24, s24, 0
	s_cmp_gt_u32 s25, 29
	s_cbranch_scc0 .LBB0_1997
	v_readlane_b32 s16, v253, 2
	v_readlane_b32 s17, v253, 3
	s_and_b64 vcc, exec, s[16:17]
	s_cbranch_vccz .LBB0_2000
	s_barrier

.LBB0_2111:
	s_add_u32 s16, s14, 0xfffc0080
	s_addc_u32 s17, s15, -1
	s_add_i32 s51, 0, 0x10000
	s_cmp_eq_u32 s50, 12
	s_cselect_b32 s21, s9, s17
	s_cselect_b32 s20, s46, s16
	s_cselect_b32 s17, s5, s49
	s_cselect_b32 s16, s47, s48
	s_add_i32 s54, 0, 0x14000
	v_add_u32_e32 v154, s51, v181
	v_add_u32_e32 v170, s54, v181
	ds_read_b128 v[130:133], v154
	ds_read_b128 v[134:137], v154 offset:1024
	ds_read_b128 v[150:153], v154 offset:2048
	ds_read_b128 v[154:157], v154 offset:3072
	ds_read_b128 v[158:161], v170
	ds_read_b128 v[162:165], v170 offset:1024
	ds_read_b128 v[166:169], v170 offset:2048
	ds_read_b128 v[170:173], v170 offset:3072
	s_add_i32 m0, s26, 0xc000
	ds_read_b128 v[174:177], v184
	ds_read_b128 v[186:189], v184 offset:1024
	ds_read_b128 v[190:193], v184 offset:2048
	ds_read_b128 v[194:197], v184 offset:3072
	ds_read_b128 v[198:201], v184 offset:4096
	ds_read_b128 v[202:205], v184 offset:5120
	ds_read_b128 v[206:209], v184 offset:6144
	ds_read_b128 v[210:213], v184 offset:7168
	global_load_lds_dwordx4 v146, s[14:15]
	s_add_i32 m0, s26, 0xe000
	s_nop 0
	global_load_lds_dwordx4 v148, s[14:15]
	s_waitcnt vmcnt(8)
	s_waitcnt lgkmcnt(0)
	s_barrier
	s_setprio 1
	s_waitcnt lgkmcnt(0)
	v_mfma_i32_16x16x64_i8 v[126:129], v[130:133], v[174:177], v[126:129]
	v_mfma_i32_16x16x64_i8 v[126:129], v[134:137], v[186:189], v[126:129]
	v_mfma_i32_16x16x64_i8 v[110:113], v[130:133], v[190:193], v[110:113]
	v_mfma_i32_16x16x64_i8 v[110:113], v[134:137], v[194:197], v[110:113]
	v_mfma_i32_16x16x64_i8 v[102:105], v[150:153], v[190:193], v[102:105]
	v_mfma_i32_16x16x64_i8 v[102:105], v[154:157], v[194:197], v[102:105]
	v_mfma_i32_16x16x64_i8 v[122:125], v[150:153], v[174:177], v[122:125]
	v_mfma_i32_16x16x64_i8 v[122:125], v[154:157], v[186:189], v[122:125]
	v_mfma_i32_16x16x64_i8 v[118:121], v[158:161], v[174:177], v[118:121]
	v_mfma_i32_16x16x64_i8 v[118:121], v[162:165], v[186:189], v[118:121]
	v_mfma_i32_16x16x64_i8 v[114:117], v[166:169], v[174:177], v[114:117]
	v_mfma_i32_16x16x64_i8 v[114:117], v[170:173], v[186:189], v[114:117]
	v_mfma_i32_16x16x64_i8 v[98:101], v[166:169], v[190:193], v[98:101]
	v_mfma_i32_16x16x64_i8 v[98:101], v[170:173], v[194:197], v[98:101]
	v_mfma_i32_16x16x64_i8 v[106:109], v[158:161], v[190:193], v[106:109]
	v_mfma_i32_16x16x64_i8 v[106:109], v[162:165], v[194:197], v[106:109]
	v_mfma_i32_16x16x64_i8 v[90:93], v[158:161], v[198:201], v[90:93]
	v_mfma_i32_16x16x64_i8 v[90:93], v[162:165], v[202:205], v[90:93]
	v_mfma_i32_16x16x64_i8 v[82:85], v[166:169], v[198:201], v[82:85]
	v_mfma_i32_16x16x64_i8 v[82:85], v[170:173], v[202:205], v[82:85]
	v_mfma_i32_16x16x64_i8 v[66:69], v[166:169], v[206:209], v[66:69]
	v_mfma_i32_16x16x64_i8 v[66:69], v[170:173], v[210:213], v[66:69]
	v_mfma_i32_16x16x64_i8 v[74:77], v[158:161], v[206:209], v[74:77]
	v_mfma_i32_16x16x64_i8 v[74:77], v[162:165], v[210:213], v[74:77]
	v_mfma_i32_16x16x64_i8 v[70:73], v[150:153], v[206:209], v[70:73]
	v_mfma_i32_16x16x64_i8 v[70:73], v[154:157], v[210:213], v[70:73]
	v_mfma_i32_16x16x64_i8 v[86:89], v[150:153], v[198:201], v[86:89]
	v_mfma_i32_16x16x64_i8 v[86:89], v[154:157], v[202:205], v[86:89]
	v_mfma_i32_16x16x64_i8 v[94:97], v[130:133], v[198:201], v[94:97]
	v_mfma_i32_16x16x64_i8 v[94:97], v[134:137], v[202:205], v[94:97]
	v_mfma_i32_16x16x64_i8 v[78:81], v[130:133], v[206:209], v[78:81]
	v_mfma_i32_16x16x64_i8 v[78:81], v[134:137], v[210:213], v[78:81]
	s_setprio 0
	s_barrier
	s_add_i32 s51, s51, s33
	v_lshl_add_u64 v[178:179], s[16:17], 0, v[0:1]
	s_mov_b32 m0, s51
	ds_read_b128 v[174:177], v184 offset:16384
	ds_read_b128 v[186:189], v184 offset:17408
	ds_read_b128 v[190:193], v184 offset:18432
	ds_read_b128 v[194:197], v184 offset:19456
	ds_read_b128 v[198:201], v184 offset:20480
	ds_read_b128 v[202:205], v184 offset:21504
	ds_read_b128 v[206:209], v184 offset:22528
	ds_read_b128 v[210:213], v184 offset:23552
	global_load_lds_dwordx4 v[178:179], off
	s_add_i32 m0, s51, 0x2000
	s_add_u32 s52, s16, 0x40000
	v_lshl_add_u64 v[220:221], s[16:17], 0, v[138:139]
	s_addc_u32 s53, s17, 0
	s_add_i32 s51, s54, s33
	global_load_lds_dwordx4 v[220:221], off
	s_mov_b32 m0, s51
	v_lshl_add_u64 v[226:227], s[20:21], 0, v[140:141]
	global_load_lds_dwordx4 v0, s[52:53]
	s_add_i32 m0, s51, 0x2000
	s_nop 0
	global_load_lds_dwordx4 v138, s[52:53]
	v_lshl_add_u64 v[224:225], s[20:21], 0, v[142:143]
	s_mov_b32 m0, s26
	s_nop 0
	global_load_lds_dwordx4 v[224:225], off
	s_mov_b32 m0, s27
	s_nop 0
	global_load_lds_dwordx4 v[226:227], off
	s_waitcnt vmcnt(8)
	s_waitcnt lgkmcnt(0)
	s_barrier
	s_setprio 1
	s_waitcnt lgkmcnt(0)
	v_mfma_i32_16x16x64_i8 v[62:65], v[130:133], v[174:177], v[62:65]
	v_mfma_i32_16x16x64_i8 v[62:65], v[134:137], v[186:189], v[62:65]
	v_mfma_i32_16x16x64_i8 v[46:49], v[130:133], v[190:193], v[46:49]
	v_mfma_i32_16x16x64_i8 v[46:49], v[134:137], v[194:197], v[46:49]
	v_mfma_i32_16x16x64_i8 v[38:41], v[150:153], v[190:193], v[38:41]
	v_mfma_i32_16x16x64_i8 v[38:41], v[154:157], v[194:197], v[38:41]
	v_mfma_i32_16x16x64_i8 v[54:57], v[150:153], v[174:177], v[54:57]
	v_mfma_i32_16x16x64_i8 v[54:57], v[154:157], v[186:189], v[54:57]
	v_mfma_i32_16x16x64_i8 v[58:61], v[158:161], v[174:177], v[58:61]
	v_mfma_i32_16x16x64_i8 v[58:61], v[162:165], v[186:189], v[58:61]
	v_mfma_i32_16x16x64_i8 v[50:53], v[166:169], v[174:177], v[50:53]
	v_mfma_i32_16x16x64_i8 v[50:53], v[170:173], v[186:189], v[50:53]
	v_mfma_i32_16x16x64_i8 v[34:37], v[166:169], v[190:193], v[34:37]
	v_mfma_i32_16x16x64_i8 v[34:37], v[170:173], v[194:197], v[34:37]
	v_mfma_i32_16x16x64_i8 v[42:45], v[158:161], v[190:193], v[42:45]
	v_mfma_i32_16x16x64_i8 v[42:45], v[162:165], v[194:197], v[42:45]
	v_mfma_i32_16x16x64_i8 v[26:29], v[158:161], v[198:201], v[26:29]
	v_mfma_i32_16x16x64_i8 v[26:29], v[162:165], v[202:205], v[26:29]
	v_mfma_i32_16x16x64_i8 v[18:21], v[166:169], v[198:201], v[18:21]
	v_mfma_i32_16x16x64_i8 v[18:21], v[170:173], v[202:205], v[18:21]
	v_mfma_i32_16x16x64_i8 v[2:5], v[166:169], v[206:209], v[2:5]
	v_mfma_i32_16x16x64_i8 v[2:5], v[170:173], v[210:213], v[2:5]
	v_mfma_i32_16x16x64_i8 v[10:13], v[158:161], v[206:209], v[10:13]
	v_mfma_i32_16x16x64_i8 v[10:13], v[162:165], v[210:213], v[10:13]
	v_mfma_i32_16x16x64_i8 v[6:9], v[150:153], v[206:209], v[6:9]
	v_mfma_i32_16x16x64_i8 v[6:9], v[154:157], v[210:213], v[6:9]
	v_mfma_i32_16x16x64_i8 v[22:25], v[150:153], v[198:201], v[22:25]
	v_mfma_i32_16x16x64_i8 v[22:25], v[154:157], v[202:205], v[22:25]
	v_mfma_i32_16x16x64_i8 v[30:33], v[130:133], v[198:201], v[30:33]
	v_mfma_i32_16x16x64_i8 v[30:33], v[134:137], v[202:205], v[30:33]
	v_mfma_i32_16x16x64_i8 v[14:17], v[130:133], v[206:209], v[14:17]
	v_mfma_i32_16x16x64_i8 v[14:17], v[134:137], v[210:213], v[14:17]
	s_setprio 0
	s_barrier
	s_add_i32 s51, 0, 0x18000
	s_add_i32 s52, 0, 0x1c000
	v_add_u32_e32 v154, s51, v181
	v_add_u32_e32 v170, s52, v181
	ds_read_b128 v[130:133], v154
	ds_read_b128 v[134:137], v154 offset:1024
	ds_read_b128 v[150:153], v154 offset:2048
	ds_read_b128 v[154:157], v154 offset:3072
	ds_read_b128 v[158:161], v170
	ds_read_b128 v[162:165], v170 offset:1024
	ds_read_b128 v[166:169], v170 offset:2048
	ds_read_b128 v[170:173], v170 offset:3072
	s_add_u32 s20, s20, 0x40000
	s_addc_u32 s21, s21, 0
	s_mov_b32 m0, s28
	ds_read_b128 v[174:177], v184 offset:32768
	ds_read_b128 v[186:189], v184 offset:33792
	ds_read_b128 v[190:193], v184 offset:34816
	ds_read_b128 v[194:197], v184 offset:35840
	ds_read_b128 v[198:201], v184 offset:36864
	ds_read_b128 v[202:205], v184 offset:37888
	ds_read_b128 v[206:209], v184 offset:38912
	ds_read_b128 v[210:213], v184 offset:39936
	global_load_lds_dwordx4 v142, s[20:21]
	s_mov_b32 m0, s29
	s_nop 0
	global_load_lds_dwordx4 v140, s[20:21]
	s_waitcnt vmcnt(8)
	s_waitcnt lgkmcnt(0)
	s_barrier
	s_setprio 1
	s_waitcnt lgkmcnt(0)
	v_mfma_i32_16x16x64_i8 v[126:129], v[130:133], v[174:177], v[126:129]
	v_mfma_i32_16x16x64_i8 v[126:129], v[134:137], v[186:189], v[126:129]
	v_mfma_i32_16x16x64_i8 v[110:113], v[130:133], v[190:193], v[110:113]
	v_mfma_i32_16x16x64_i8 v[110:113], v[134:137], v[194:197], v[110:113]
	v_mfma_i32_16x16x64_i8 v[102:105], v[150:153], v[190:193], v[102:105]
	v_mfma_i32_16x16x64_i8 v[102:105], v[154:157], v[194:197], v[102:105]
	v_mfma_i32_16x16x64_i8 v[122:125], v[150:153], v[174:177], v[122:125]
	v_mfma_i32_16x16x64_i8 v[122:125], v[154:157], v[186:189], v[122:125]
	v_mfma_i32_16x16x64_i8 v[118:121], v[158:161], v[174:177], v[118:121]
	v_mfma_i32_16x16x64_i8 v[118:121], v[162:165], v[186:189], v[118:121]
	v_mfma_i32_16x16x64_i8 v[114:117], v[166:169], v[174:177], v[114:117]
	v_mfma_i32_16x16x64_i8 v[114:117], v[170:173], v[186:189], v[114:117]
	v_mfma_i32_16x16x64_i8 v[98:101], v[166:169], v[190:193], v[98:101]
	v_mfma_i32_16x16x64_i8 v[98:101], v[170:173], v[194:197], v[98:101]
	v_mfma_i32_16x16x64_i8 v[106:109], v[158:161], v[190:193], v[106:109]
	v_mfma_i32_16x16x64_i8 v[106:109], v[162:165], v[194:197], v[106:109]
	v_mfma_i32_16x16x64_i8 v[90:93], v[158:161], v[198:201], v[90:93]
	v_mfma_i32_16x16x64_i8 v[90:93], v[162:165], v[202:205], v[90:93]
	v_mfma_i32_16x16x64_i8 v[82:85], v[166:169], v[198:201], v[82:85]
	v_mfma_i32_16x16x64_i8 v[82:85], v[170:173], v[202:205], v[82:85]
	v_mfma_i32_16x16x64_i8 v[66:69], v[166:169], v[206:209], v[66:69]
	v_mfma_i32_16x16x64_i8 v[66:69], v[170:173], v[210:213], v[66:69]
	v_mfma_i32_16x16x64_i8 v[74:77], v[158:161], v[206:209], v[74:77]
	v_mfma_i32_16x16x64_i8 v[74:77], v[162:165], v[210:213], v[74:77]
	v_mfma_i32_16x16x64_i8 v[70:73], v[150:153], v[206:209], v[70:73]
	v_mfma_i32_16x16x64_i8 v[70:73], v[154:157], v[210:213], v[70:73]
	v_mfma_i32_16x16x64_i8 v[86:89], v[150:153], v[198:201], v[86:89]
	v_mfma_i32_16x16x64_i8 v[86:89], v[154:157], v[202:205], v[86:89]
	v_mfma_i32_16x16x64_i8 v[94:97], v[130:133], v[198:201], v[94:97]
	v_mfma_i32_16x16x64_i8 v[94:97], v[134:137], v[202:205], v[94:97]
	v_mfma_i32_16x16x64_i8 v[78:81], v[130:133], v[206:209], v[78:81]
	v_mfma_i32_16x16x64_i8 v[78:81], v[134:137], v[210:213], v[78:81]
	s_setprio 0
	s_barrier
	s_add_i32 s20, s51, s33
	v_lshl_add_u64 v[178:179], v[178:179], 0, s[30:31]
	s_mov_b32 m0, s20
	ds_read_b128 v[174:177], v184 offset:49152
	ds_read_b128 v[186:189], v184 offset:50176
	ds_read_b128 v[190:193], v184 offset:51200
	ds_read_b128 v[194:197], v184 offset:52224
	ds_read_b128 v[198:201], v184 offset:53248
	ds_read_b128 v[202:205], v184 offset:54272
	ds_read_b128 v[206:209], v184 offset:55296
	ds_read_b128 v[210:213], v184 offset:56320
	global_load_lds_dwordx4 v[178:179], off
	s_add_i32 m0, s20, 0x2000
	s_add_u32 s16, s16, 0x40080
	v_lshl_add_u64 v[178:179], v[220:221], 0, s[30:31]
	s_addc_u32 s17, s17, 0
	s_add_i32 s20, s52, s33
	global_load_lds_dwordx4 v[178:179], off
	s_mov_b32 m0, s20
	s_nop 0
	global_load_lds_dwordx4 v0, s[16:17]
	s_add_i32 m0, s20, 0x2000
	s_nop 0
	global_load_lds_dwordx4 v138, s[16:17]
	v_lshl_add_u64 v[178:179], v[224:225], 0, s[30:31]
	s_mov_b32 m0, s34
	s_nop 0
	global_load_lds_dwordx4 v[178:179], off
	v_lshl_add_u64 v[178:179], v[226:227], 0, s[30:31]
	s_mov_b32 m0, s35
	s_nop 0
	global_load_lds_dwordx4 v[178:179], off
	s_waitcnt vmcnt(8)
	s_waitcnt lgkmcnt(0)
	s_barrier
	s_setprio 1
	s_waitcnt lgkmcnt(0)
	v_mfma_i32_16x16x64_i8 v[62:65], v[130:133], v[174:177], v[62:65]
	v_mfma_i32_16x16x64_i8 v[62:65], v[134:137], v[186:189], v[62:65]
	v_mfma_i32_16x16x64_i8 v[46:49], v[130:133], v[190:193], v[46:49]
	v_mfma_i32_16x16x64_i8 v[46:49], v[134:137], v[194:197], v[46:49]
	v_mfma_i32_16x16x64_i8 v[38:41], v[150:153], v[190:193], v[38:41]
	v_mfma_i32_16x16x64_i8 v[38:41], v[154:157], v[194:197], v[38:41]
	v_mfma_i32_16x16x64_i8 v[54:57], v[150:153], v[174:177], v[54:57]
	v_mfma_i32_16x16x64_i8 v[54:57], v[154:157], v[186:189], v[54:57]
	v_mfma_i32_16x16x64_i8 v[58:61], v[158:161], v[174:177], v[58:61]
	v_mfma_i32_16x16x64_i8 v[58:61], v[162:165], v[186:189], v[58:61]
	v_mfma_i32_16x16x64_i8 v[50:53], v[166:169], v[174:177], v[50:53]
	v_mfma_i32_16x16x64_i8 v[50:53], v[170:173], v[186:189], v[50:53]
	v_mfma_i32_16x16x64_i8 v[34:37], v[166:169], v[190:193], v[34:37]
	v_mfma_i32_16x16x64_i8 v[34:37], v[170:173], v[194:197], v[34:37]
	v_mfma_i32_16x16x64_i8 v[42:45], v[158:161], v[190:193], v[42:45]
	v_mfma_i32_16x16x64_i8 v[42:45], v[162:165], v[194:197], v[42:45]
	v_mfma_i32_16x16x64_i8 v[26:29], v[158:161], v[198:201], v[26:29]
	v_mfma_i32_16x16x64_i8 v[26:29], v[162:165], v[202:205], v[26:29]
	v_mfma_i32_16x16x64_i8 v[18:21], v[166:169], v[198:201], v[18:21]
	v_mfma_i32_16x16x64_i8 v[18:21], v[170:173], v[202:205], v[18:21]
	v_mfma_i32_16x16x64_i8 v[2:5], v[166:169], v[206:209], v[2:5]
	v_mfma_i32_16x16x64_i8 v[2:5], v[170:173], v[210:213], v[2:5]
	v_mfma_i32_16x16x64_i8 v[10:13], v[158:161], v[206:209], v[10:13]
	v_mfma_i32_16x16x64_i8 v[10:13], v[162:165], v[210:213], v[10:13]
	v_mfma_i32_16x16x64_i8 v[6:9], v[150:153], v[206:209], v[6:9]
	v_mfma_i32_16x16x64_i8 v[6:9], v[154:157], v[210:213], v[6:9]
	v_mfma_i32_16x16x64_i8 v[22:25], v[150:153], v[198:201], v[22:25]
	v_mfma_i32_16x16x64_i8 v[22:25], v[154:157], v[202:205], v[22:25]
	v_mfma_i32_16x16x64_i8 v[30:33], v[130:133], v[198:201], v[30:33]
	v_mfma_i32_16x16x64_i8 v[30:33], v[134:137], v[202:205], v[30:33]
	v_mfma_i32_16x16x64_i8 v[14:17], v[130:133], v[206:209], v[14:17]
	v_mfma_i32_16x16x64_i8 v[14:17], v[134:137], v[210:213], v[14:17]
	s_setprio 0
	s_barrier
	s_add_i32 s50, s50, 2
	s_add_u32 s14, s14, 0x100
	s_addc_u32 s15, s15, 0
	s_add_u32 s48, s48, 0x100
	s_addc_u32 s49, s49, 0
	s_cmp_gt_u32 s50, 13
	s_cbranch_scc0 .LBB0_2111
	v_readlane_b32 s14, v253, 2
	v_readlane_b32 s15, v253, 3
	s_and_b64 vcc, exec, s[14:15]
	s_cbranch_vccz .LBB0_2114
	s_barrier

.LBB0_2193:
	s_add_u32 s16, s12, 0x100
	s_addc_u32 s17, s13, 0
	s_add_i32 s67, 0, 0x10000
	s_cmpk_eq_i32 s19, 0x54
	s_cselect_b32 s23, s7, s17
	s_cselect_b32 s22, s6, s16
	s_cselect_b32 s21, s11, s18
	s_cselect_b32 s20, s10, s15
	s_add_i32 s68, 0, 0x14000
	v_add_u32_e32 v142, s67, v205
	v_add_u32_e32 v162, s68, v205
	ds_read_b128 v[130:133], v142
	ds_read_b128 v[134:137], v142 offset:1024
	ds_read_b128 v[138:141], v142 offset:2048
	ds_read_b128 v[142:145], v142 offset:3072
	ds_read_b128 v[146:149], v162
	ds_read_b128 v[150:153], v162 offset:1024
	ds_read_b128 v[154:157], v162 offset:2048
	ds_read_b128 v[162:165], v162 offset:3072
	s_add_i32 m0, s28, 0xc000
	ds_read_b128 v[166:169], v230
	ds_read_b128 v[170:173], v230 offset:1024
	ds_read_b128 v[184:187], v230 offset:2048
	ds_read_b128 v[188:191], v230 offset:3072
	ds_read_b128 v[192:195], v230 offset:4096
	ds_read_b128 v[196:199], v230 offset:5120
	ds_read_b128 v[200:203], v230 offset:6144
	ds_read_b128 v[232:235], v230 offset:7168
	global_load_lds_dwordx4 v180, s[12:13]
	s_add_i32 m0, s28, 0xe000
	s_nop 0
	global_load_lds_dwordx4 v182, s[12:13]
	s_waitcnt vmcnt(8)
	s_waitcnt lgkmcnt(0)
	s_barrier
	s_setprio 1
	s_waitcnt lgkmcnt(0)
	v_mfma_f32_16x16x32_bf16 v[126:129], v[130:133], v[166:169], v[126:129]
	v_mfma_f32_16x16x32_bf16 v[126:129], v[134:137], v[170:173], v[126:129]
	v_mfma_f32_16x16x32_bf16 v[118:121], v[130:133], v[184:187], v[118:121]
	v_mfma_f32_16x16x32_bf16 v[118:121], v[134:137], v[188:191], v[118:121]
	v_mfma_f32_16x16x32_bf16 v[86:89], v[138:141], v[184:187], v[86:89]
	v_mfma_f32_16x16x32_bf16 v[86:89], v[142:145], v[188:191], v[86:89]
	v_mfma_f32_16x16x32_bf16 v[74:77], v[138:141], v[166:169], v[74:77]
	v_mfma_f32_16x16x32_bf16 v[74:77], v[142:145], v[170:173], v[74:77]
	v_mfma_f32_16x16x32_bf16 v[122:125], v[146:149], v[166:169], v[122:125]
	v_mfma_f32_16x16x32_bf16 v[122:125], v[150:153], v[170:173], v[122:125]
	v_mfma_f32_16x16x32_bf16 v[82:85], v[154:157], v[166:169], v[82:85]
	v_mfma_f32_16x16x32_bf16 v[82:85], v[162:165], v[170:173], v[82:85]
	v_mfma_f32_16x16x32_bf16 v[90:93], v[154:157], v[184:187], v[90:93]
	v_mfma_f32_16x16x32_bf16 v[90:93], v[162:165], v[188:191], v[90:93]
	v_mfma_f32_16x16x32_bf16 v[114:117], v[146:149], v[184:187], v[114:117]
	v_mfma_f32_16x16x32_bf16 v[114:117], v[150:153], v[188:191], v[114:117]
	v_mfma_f32_16x16x32_bf16 v[106:109], v[146:149], v[192:195], v[106:109]
	v_mfma_f32_16x16x32_bf16 v[106:109], v[150:153], v[196:199], v[106:109]
	v_mfma_f32_16x16x32_bf16 v[70:73], v[154:157], v[192:195], v[70:73]
	v_mfma_f32_16x16x32_bf16 v[70:73], v[162:165], v[196:199], v[70:73]
	v_mfma_f32_16x16x32_bf16 v[42:45], v[154:157], v[200:203], v[42:45]
	v_mfma_f32_16x16x32_bf16 v[42:45], v[162:165], v[232:235], v[42:45]
	v_mfma_f32_16x16x32_bf16 v[98:101], v[146:149], v[200:203], v[98:101]
	v_mfma_f32_16x16x32_bf16 v[98:101], v[150:153], v[232:235], v[98:101]
	v_mfma_f32_16x16x32_bf16 v[38:41], v[138:141], v[200:203], v[38:41]
	v_mfma_f32_16x16x32_bf16 v[38:41], v[142:145], v[232:235], v[38:41]
	v_mfma_f32_16x16x32_bf16 v[66:69], v[138:141], v[192:195], v[66:69]
	v_mfma_f32_16x16x32_bf16 v[66:69], v[142:145], v[196:199], v[66:69]
	v_mfma_f32_16x16x32_bf16 v[110:113], v[130:133], v[192:195], v[110:113]
	v_mfma_f32_16x16x32_bf16 v[110:113], v[134:137], v[196:199], v[110:113]
	v_mfma_f32_16x16x32_bf16 v[102:105], v[130:133], v[200:203], v[102:105]
	v_mfma_f32_16x16x32_bf16 v[102:105], v[134:137], v[232:235], v[102:105]
	s_setprio 0
	s_barrier
	s_add_i32 s12, s67, s33
	v_lshl_add_u64 v[212:213], s[20:21], 0, v[0:1]
	s_mov_b32 m0, s12
	ds_read_b128 v[166:169], v230 offset:16384
	ds_read_b128 v[170:173], v230 offset:17408
	ds_read_b128 v[184:187], v230 offset:18432
	ds_read_b128 v[188:191], v230 offset:19456
	ds_read_b128 v[192:195], v230 offset:20480
	ds_read_b128 v[196:199], v230 offset:21504
	ds_read_b128 v[200:203], v230 offset:22528
	ds_read_b128 v[232:235], v230 offset:23552
	global_load_lds_dwordx4 v[212:213], off
	s_add_i32 m0, s12, 0x2000
	s_add_u32 s12, s20, 0x160000
	v_lshl_add_u64 v[220:221], s[20:21], 0, v[158:159]
	s_addc_u32 s13, s21, 0
	s_add_i32 s67, s68, s33
	global_load_lds_dwordx4 v[220:221], off
	s_mov_b32 m0, s67
	v_lshl_add_u64 v[238:239], s[22:23], 0, v[160:161]
	global_load_lds_dwordx4 v0, s[12:13]
	s_add_i32 m0, s67, 0x2000
	s_nop 0
	global_load_lds_dwordx4 v158, s[12:13]
	v_lshl_add_u64 v[236:237], s[22:23], 0, v[174:175]
	s_mov_b32 m0, s28
	s_nop 0
	global_load_lds_dwordx4 v[236:237], off
	s_mov_b32 m0, s29
	s_nop 0
	global_load_lds_dwordx4 v[238:239], off
	s_waitcnt vmcnt(8)
	s_waitcnt lgkmcnt(0)
	s_barrier
	s_setprio 1
	s_waitcnt lgkmcnt(0)
	v_mfma_f32_16x16x32_bf16 v[94:97], v[130:133], v[166:169], v[94:97]
	v_mfma_f32_16x16x32_bf16 v[94:97], v[134:137], v[170:173], v[94:97]
	v_mfma_f32_16x16x32_bf16 v[62:65], v[130:133], v[184:187], v[62:65]
	v_mfma_f32_16x16x32_bf16 v[62:65], v[134:137], v[188:191], v[62:65]
	v_mfma_f32_16x16x32_bf16 v[30:33], v[138:141], v[184:187], v[30:33]
	v_mfma_f32_16x16x32_bf16 v[30:33], v[142:145], v[188:191], v[30:33]
	v_mfma_f32_16x16x32_bf16 v[50:53], v[138:141], v[166:169], v[50:53]
	v_mfma_f32_16x16x32_bf16 v[50:53], v[142:145], v[170:173], v[50:53]
	v_mfma_f32_16x16x32_bf16 v[78:81], v[146:149], v[166:169], v[78:81]
	v_mfma_f32_16x16x32_bf16 v[78:81], v[150:153], v[170:173], v[78:81]
	v_mfma_f32_16x16x32_bf16 v[58:61], v[154:157], v[166:169], v[58:61]
	v_mfma_f32_16x16x32_bf16 v[58:61], v[162:165], v[170:173], v[58:61]
	v_mfma_f32_16x16x32_bf16 v[34:37], v[154:157], v[184:187], v[34:37]
	v_mfma_f32_16x16x32_bf16 v[34:37], v[162:165], v[188:191], v[34:37]
	v_mfma_f32_16x16x32_bf16 v[54:57], v[146:149], v[184:187], v[54:57]
	v_mfma_f32_16x16x32_bf16 v[54:57], v[150:153], v[188:191], v[54:57]
	v_mfma_f32_16x16x32_bf16 v[26:29], v[146:149], v[192:195], v[26:29]
	v_mfma_f32_16x16x32_bf16 v[26:29], v[150:153], v[196:199], v[26:29]
	v_mfma_f32_16x16x32_bf16 v[14:17], v[154:157], v[192:195], v[14:17]
	v_mfma_f32_16x16x32_bf16 v[14:17], v[162:165], v[196:199], v[14:17]
	v_mfma_f32_16x16x32_bf16 v[6:9], v[154:157], v[200:203], v[6:9]
	v_mfma_f32_16x16x32_bf16 v[6:9], v[162:165], v[232:235], v[6:9]
	v_mfma_f32_16x16x32_bf16 v[18:21], v[146:149], v[200:203], v[18:21]
	v_mfma_f32_16x16x32_bf16 v[18:21], v[150:153], v[232:235], v[18:21]
	v_mfma_f32_16x16x32_bf16 v[2:5], v[138:141], v[200:203], v[2:5]
	v_mfma_f32_16x16x32_bf16 v[2:5], v[142:145], v[232:235], v[2:5]
	v_mfma_f32_16x16x32_bf16 v[10:13], v[138:141], v[192:195], v[10:13]
	v_mfma_f32_16x16x32_bf16 v[10:13], v[142:145], v[196:199], v[10:13]
	v_mfma_f32_16x16x32_bf16 v[46:49], v[130:133], v[192:195], v[46:49]
	v_mfma_f32_16x16x32_bf16 v[46:49], v[134:137], v[196:199], v[46:49]
	v_mfma_f32_16x16x32_bf16 v[22:25], v[130:133], v[200:203], v[22:25]
	v_mfma_f32_16x16x32_bf16 v[22:25], v[134:137], v[232:235], v[22:25]
	s_setprio 0
	s_barrier
	s_add_i32 s67, 0, 0x18000
	s_add_i32 s68, 0, 0x1c000
	v_add_u32_e32 v142, s67, v205
	v_add_u32_e32 v162, s68, v205
	ds_read_b128 v[130:133], v142
	ds_read_b128 v[134:137], v142 offset:1024
	ds_read_b128 v[138:141], v142 offset:2048
	ds_read_b128 v[142:145], v142 offset:3072
	ds_read_b128 v[146:149], v162
	ds_read_b128 v[150:153], v162 offset:1024
	ds_read_b128 v[154:157], v162 offset:2048
	ds_read_b128 v[162:165], v162 offset:3072
	s_add_u32 s12, s22, 0x160000
	s_addc_u32 s13, s23, 0
	s_mov_b32 m0, s34
	ds_read_b128 v[166:169], v230 offset:32768
	ds_read_b128 v[170:173], v230 offset:33792
	ds_read_b128 v[184:187], v230 offset:34816
	ds_read_b128 v[188:191], v230 offset:35840
	ds_read_b128 v[192:195], v230 offset:36864
	ds_read_b128 v[196:199], v230 offset:37888
	ds_read_b128 v[200:203], v230 offset:38912
	ds_read_b128 v[232:235], v230 offset:39936
	global_load_lds_dwordx4 v174, s[12:13]
	s_mov_b32 m0, s35
	s_nop 0
	global_load_lds_dwordx4 v160, s[12:13]
	s_waitcnt vmcnt(8)
	s_waitcnt lgkmcnt(0)
	s_barrier
	s_setprio 1
	s_waitcnt lgkmcnt(0)
	v_mfma_f32_16x16x32_bf16 v[126:129], v[130:133], v[166:169], v[126:129]
	v_mfma_f32_16x16x32_bf16 v[126:129], v[134:137], v[170:173], v[126:129]
	v_mfma_f32_16x16x32_bf16 v[118:121], v[130:133], v[184:187], v[118:121]
	v_mfma_f32_16x16x32_bf16 v[118:121], v[134:137], v[188:191], v[118:121]
	v_mfma_f32_16x16x32_bf16 v[86:89], v[138:141], v[184:187], v[86:89]
	v_mfma_f32_16x16x32_bf16 v[86:89], v[142:145], v[188:191], v[86:89]
	v_mfma_f32_16x16x32_bf16 v[74:77], v[138:141], v[166:169], v[74:77]
	v_mfma_f32_16x16x32_bf16 v[74:77], v[142:145], v[170:173], v[74:77]
	v_mfma_f32_16x16x32_bf16 v[122:125], v[146:149], v[166:169], v[122:125]
	v_mfma_f32_16x16x32_bf16 v[122:125], v[150:153], v[170:173], v[122:125]
	v_mfma_f32_16x16x32_bf16 v[82:85], v[154:157], v[166:169], v[82:85]
	v_mfma_f32_16x16x32_bf16 v[82:85], v[162:165], v[170:173], v[82:85]
	v_mfma_f32_16x16x32_bf16 v[90:93], v[154:157], v[184:187], v[90:93]
	v_mfma_f32_16x16x32_bf16 v[90:93], v[162:165], v[188:191], v[90:93]
	v_mfma_f32_16x16x32_bf16 v[114:117], v[146:149], v[184:187], v[114:117]
	v_mfma_f32_16x16x32_bf16 v[114:117], v[150:153], v[188:191], v[114:117]
	v_mfma_f32_16x16x32_bf16 v[106:109], v[146:149], v[192:195], v[106:109]
	v_mfma_f32_16x16x32_bf16 v[106:109], v[150:153], v[196:199], v[106:109]
	v_mfma_f32_16x16x32_bf16 v[70:73], v[154:157], v[192:195], v[70:73]
	v_mfma_f32_16x16x32_bf16 v[70:73], v[162:165], v[196:199], v[70:73]
	v_mfma_f32_16x16x32_bf16 v[42:45], v[154:157], v[200:203], v[42:45]
	v_mfma_f32_16x16x32_bf16 v[42:45], v[162:165], v[232:235], v[42:45]
	v_mfma_f32_16x16x32_bf16 v[98:101], v[146:149], v[200:203], v[98:101]
	v_mfma_f32_16x16x32_bf16 v[98:101], v[150:153], v[232:235], v[98:101]
	v_mfma_f32_16x16x32_bf16 v[38:41], v[138:141], v[200:203], v[38:41]
	v_mfma_f32_16x16x32_bf16 v[38:41], v[142:145], v[232:235], v[38:41]
	v_mfma_f32_16x16x32_bf16 v[66:69], v[138:141], v[192:195], v[66:69]
	v_mfma_f32_16x16x32_bf16 v[66:69], v[142:145], v[196:199], v[66:69]
	v_mfma_f32_16x16x32_bf16 v[110:113], v[130:133], v[192:195], v[110:113]
	v_mfma_f32_16x16x32_bf16 v[110:113], v[134:137], v[196:199], v[110:113]
	v_mfma_f32_16x16x32_bf16 v[102:105], v[130:133], v[200:203], v[102:105]
	v_mfma_f32_16x16x32_bf16 v[102:105], v[134:137], v[232:235], v[102:105]
	s_setprio 0
	s_barrier
	s_add_i32 s12, s67, s33
	v_lshl_add_u64 v[212:213], v[212:213], 0, s[30:31]
	s_mov_b32 m0, s12
	ds_read_b128 v[166:169], v230 offset:49152
	ds_read_b128 v[170:173], v230 offset:50176
	ds_read_b128 v[184:187], v230 offset:51200
	ds_read_b128 v[188:191], v230 offset:52224
	ds_read_b128 v[192:195], v230 offset:53248
	ds_read_b128 v[196:199], v230 offset:54272
	ds_read_b128 v[200:203], v230 offset:55296
	ds_read_b128 v[232:235], v230 offset:56320
	global_load_lds_dwordx4 v[212:213], off
	s_add_i32 m0, s12, 0x2000
	s_add_u32 s12, s20, 0x160080
	v_lshl_add_u64 v[212:213], v[220:221], 0, s[30:31]
	s_addc_u32 s13, s21, 0
	s_add_i32 s20, s68, s33
	global_load_lds_dwordx4 v[212:213], off
	s_mov_b32 m0, s20
	s_nop 0
	global_load_lds_dwordx4 v0, s[12:13]
	s_add_i32 m0, s20, 0x2000
	s_nop 0
	global_load_lds_dwordx4 v158, s[12:13]
	v_lshl_add_u64 v[212:213], v[236:237], 0, s[30:31]
	s_mov_b32 m0, s55
	s_nop 0
	global_load_lds_dwordx4 v[212:213], off
	v_lshl_add_u64 v[212:213], v[238:239], 0, s[30:31]
	s_mov_b32 m0, s56
	s_nop 0
	global_load_lds_dwordx4 v[212:213], off
	s_waitcnt vmcnt(8)
	s_waitcnt lgkmcnt(0)
	s_barrier
	s_setprio 1
	s_waitcnt lgkmcnt(0)
	v_mfma_f32_16x16x32_bf16 v[94:97], v[130:133], v[166:169], v[94:97]
	v_mfma_f32_16x16x32_bf16 v[94:97], v[134:137], v[170:173], v[94:97]
	v_mfma_f32_16x16x32_bf16 v[62:65], v[130:133], v[184:187], v[62:65]
	v_mfma_f32_16x16x32_bf16 v[62:65], v[134:137], v[188:191], v[62:65]
	v_mfma_f32_16x16x32_bf16 v[30:33], v[138:141], v[184:187], v[30:33]
	v_mfma_f32_16x16x32_bf16 v[30:33], v[142:145], v[188:191], v[30:33]
	v_mfma_f32_16x16x32_bf16 v[50:53], v[138:141], v[166:169], v[50:53]
	v_mfma_f32_16x16x32_bf16 v[50:53], v[142:145], v[170:173], v[50:53]
	v_mfma_f32_16x16x32_bf16 v[78:81], v[146:149], v[166:169], v[78:81]
	v_mfma_f32_16x16x32_bf16 v[78:81], v[150:153], v[170:173], v[78:81]
	v_mfma_f32_16x16x32_bf16 v[58:61], v[154:157], v[166:169], v[58:61]
	v_mfma_f32_16x16x32_bf16 v[58:61], v[162:165], v[170:173], v[58:61]
	v_mfma_f32_16x16x32_bf16 v[34:37], v[154:157], v[184:187], v[34:37]
	v_mfma_f32_16x16x32_bf16 v[34:37], v[162:165], v[188:191], v[34:37]
	v_mfma_f32_16x16x32_bf16 v[54:57], v[146:149], v[184:187], v[54:57]
	v_mfma_f32_16x16x32_bf16 v[54:57], v[150:153], v[188:191], v[54:57]
	v_mfma_f32_16x16x32_bf16 v[26:29], v[146:149], v[192:195], v[26:29]
	v_mfma_f32_16x16x32_bf16 v[26:29], v[150:153], v[196:199], v[26:29]
	v_mfma_f32_16x16x32_bf16 v[14:17], v[154:157], v[192:195], v[14:17]
	v_mfma_f32_16x16x32_bf16 v[14:17], v[162:165], v[196:199], v[14:17]
	v_mfma_f32_16x16x32_bf16 v[6:9], v[154:157], v[200:203], v[6:9]
	v_mfma_f32_16x16x32_bf16 v[6:9], v[162:165], v[232:235], v[6:9]
	v_mfma_f32_16x16x32_bf16 v[18:21], v[146:149], v[200:203], v[18:21]
	v_mfma_f32_16x16x32_bf16 v[18:21], v[150:153], v[232:235], v[18:21]
	v_mfma_f32_16x16x32_bf16 v[2:5], v[138:141], v[200:203], v[2:5]
	v_mfma_f32_16x16x32_bf16 v[2:5], v[142:145], v[232:235], v[2:5]
	v_mfma_f32_16x16x32_bf16 v[10:13], v[138:141], v[192:195], v[10:13]
	v_mfma_f32_16x16x32_bf16 v[10:13], v[142:145], v[196:199], v[10:13]
	v_mfma_f32_16x16x32_bf16 v[46:49], v[130:133], v[192:195], v[46:49]
	v_mfma_f32_16x16x32_bf16 v[46:49], v[134:137], v[196:199], v[46:49]
	v_mfma_f32_16x16x32_bf16 v[22:25], v[130:133], v[200:203], v[22:25]
	v_mfma_f32_16x16x32_bf16 v[22:25], v[134:137], v[232:235], v[22:25]
	s_setprio 0
	s_barrier
	s_add_i32 s19, s19, 2
	s_add_u32 s15, s15, 0x100
	s_addc_u32 s18, s18, 0
	s_cmpk_gt_u32 s19, 0x55
	s_mov_b64 s[12:13], s[16:17]
	s_cbranch_scc0 .LBB0_2193
	v_readlane_b32 s12, v253, 2
	v_readlane_b32 s13, v253, 3
	s_and_b64 vcc, exec, s[12:13]
	s_cbranch_vccz .LBB0_2196
	s_barrier
